# added merged 16-byte z stores in the w_in epilogue (ds_swizzle lane exchange)
# baseline (speedup 1.0000x reference)
.LBB0_412:
	ds_read_b128 v[128:131], v170
	ds_read_b128 v[132:135], v170 offset:1024
	ds_read_b128 v[164:167], v170 offset:2048
	ds_read_b128 v[176:179], v170 offset:3072
	s_add_u32 s8, s6, 0xfffc0080
	s_addc_u32 s9, s7, -1
	s_cmp_eq_u32 s38, 12
	s_cselect_b32 s11, s25, s9
	s_cselect_b32 s10, s31, s8
	s_cselect_b32 s9, s23, s36
	s_cselect_b32 s8, s34, s35
	v_lshl_add_u64 v[168:169], s[6:7], 0, v[158:159]
	s_add_i32 m0, s49, 0xc000
	ds_read_b128 v[180:183], v171
	ds_read_b128 v[184:187], v171 offset:1024
	ds_read_b128 v[188:191], v171 offset:2048
	ds_read_b128 v[192:195], v171 offset:3072
	ds_read_b128 v[196:199], v171 offset:4096
	ds_read_b128 v[200:203], v171 offset:5120
	ds_read_b128 v[204:207], v171 offset:6144
	ds_read_b128 v[208:211], v171 offset:7168
	global_load_lds_dwordx4 v[168:169], off
	v_lshl_add_u64 v[168:169], s[6:7], 0, v[156:157]
	s_add_i32 m0, s49, 0xe000
	s_nop 0
	global_load_lds_dwordx4 v[168:169], off
	s_waitcnt lgkmcnt(8)
	s_barrier
	s_waitcnt lgkmcnt(0)
	s_setprio 1
	s_waitcnt lgkmcnt(0)
	v_mfma_f32_16x16x32_bf16 v[124:127], v[128:131], v[180:183], v[124:127]
	v_mfma_f32_16x16x32_bf16 v[120:123], v[164:167], v[180:183], v[120:123]
	v_mfma_f32_16x16x32_bf16 v[108:111], v[128:131], v[188:191], v[108:111]
	v_mfma_f32_16x16x32_bf16 v[104:107], v[164:167], v[188:191], v[104:107]
	v_mfma_f32_16x16x32_bf16 v[92:95], v[128:131], v[196:199], v[92:95]
	v_mfma_f32_16x16x32_bf16 v[88:91], v[164:167], v[196:199], v[88:91]
	v_mfma_f32_16x16x32_bf16 v[76:79], v[128:131], v[204:207], v[76:79]
	v_mfma_f32_16x16x32_bf16 v[72:75], v[164:167], v[204:207], v[72:75]
	v_mfma_f32_16x16x32_bf16 v[124:127], v[132:135], v[184:187], v[124:127]
	v_mfma_f32_16x16x32_bf16 v[120:123], v[176:179], v[184:187], v[120:123]
	v_mfma_f32_16x16x32_bf16 v[108:111], v[132:135], v[192:195], v[108:111]
	v_mfma_f32_16x16x32_bf16 v[104:107], v[176:179], v[192:195], v[104:107]
	v_mfma_f32_16x16x32_bf16 v[92:95], v[132:135], v[200:203], v[92:95]
	v_mfma_f32_16x16x32_bf16 v[88:91], v[176:179], v[200:203], v[88:91]
	v_mfma_f32_16x16x32_bf16 v[76:79], v[132:135], v[208:211], v[76:79]
	v_mfma_f32_16x16x32_bf16 v[72:75], v[176:179], v[208:211], v[72:75]
	s_setprio 0
	s_barrier
	s_add_i32 s39, s58, s48
	v_lshl_add_u64 v[168:169], s[8:9], 0, v[138:139]
	s_mov_b32 m0, s39
	ds_read_b128 v[212:215], v172
	ds_read_b128 v[216:219], v172 offset:1024
	ds_read_b128 v[220:223], v172 offset:2048
	ds_read_b128 v[224:227], v172 offset:3072
	global_load_lds_dwordx4 v[168:169], off
	v_lshl_add_u64 v[228:229], s[8:9], 0, v[136:137]
	s_add_i32 m0, s39, 0x2000
	s_nop 0
	global_load_lds_dwordx4 v[228:229], off
	s_barrier
	s_waitcnt lgkmcnt(0)
	s_setprio 1
	s_waitcnt lgkmcnt(0)
	v_mfma_f32_16x16x32_bf16 v[116:119], v[212:215], v[180:183], v[116:119]
	v_mfma_f32_16x16x32_bf16 v[112:115], v[220:223], v[180:183], v[112:115]
	v_mfma_f32_16x16x32_bf16 v[100:103], v[212:215], v[188:191], v[100:103]
	v_mfma_f32_16x16x32_bf16 v[96:99], v[220:223], v[188:191], v[96:99]
	v_mfma_f32_16x16x32_bf16 v[84:87], v[212:215], v[196:199], v[84:87]
	v_mfma_f32_16x16x32_bf16 v[80:83], v[220:223], v[196:199], v[80:83]
	v_mfma_f32_16x16x32_bf16 v[68:71], v[212:215], v[204:207], v[68:71]
	v_mfma_f32_16x16x32_bf16 v[64:67], v[220:223], v[204:207], v[64:67]
	v_mfma_f32_16x16x32_bf16 v[116:119], v[216:219], v[184:187], v[116:119]
	v_mfma_f32_16x16x32_bf16 v[112:115], v[224:227], v[184:187], v[112:115]
	v_mfma_f32_16x16x32_bf16 v[100:103], v[216:219], v[192:195], v[100:103]
	v_mfma_f32_16x16x32_bf16 v[96:99], v[224:227], v[192:195], v[96:99]
	v_mfma_f32_16x16x32_bf16 v[84:87], v[216:219], v[200:203], v[84:87]
	v_mfma_f32_16x16x32_bf16 v[80:83], v[224:227], v[200:203], v[80:83]
	v_mfma_f32_16x16x32_bf16 v[68:71], v[216:219], v[208:211], v[68:71]
	v_mfma_f32_16x16x32_bf16 v[64:67], v[224:227], v[208:211], v[64:67]
	s_setprio 0
	s_mov_b32 m0, s49
	v_lshl_add_u64 v[230:231], s[10:11], 0, v[138:139]
	s_barrier
	ds_read_b128 v[180:183], v171 offset:16384
	ds_read_b128 v[184:187], v171 offset:17408
	ds_read_b128 v[188:191], v171 offset:18432
	ds_read_b128 v[192:195], v171 offset:19456
	ds_read_b128 v[196:199], v171 offset:20480
	ds_read_b128 v[200:203], v171 offset:21504
	ds_read_b128 v[204:207], v171 offset:22528
	ds_read_b128 v[208:211], v171 offset:23552
	global_load_lds_dwordx4 v[230:231], off
	v_lshl_add_u64 v[232:233], s[10:11], 0, v[136:137]
	s_mov_b32 m0, s50
	s_nop 0
	global_load_lds_dwordx4 v[232:233], off
	s_barrier
	s_waitcnt lgkmcnt(0)
	s_setprio 1
	s_waitcnt lgkmcnt(0)
	v_mfma_f32_16x16x32_bf16 v[60:63], v[128:131], v[180:183], v[60:63]
	v_mfma_f32_16x16x32_bf16 v[56:59], v[164:167], v[180:183], v[56:59]
	v_mfma_f32_16x16x32_bf16 v[44:47], v[128:131], v[188:191], v[44:47]
	v_mfma_f32_16x16x32_bf16 v[40:43], v[164:167], v[188:191], v[40:43]
	v_mfma_f32_16x16x32_bf16 v[28:31], v[128:131], v[196:199], v[28:31]
	v_mfma_f32_16x16x32_bf16 v[24:27], v[164:167], v[196:199], v[24:27]
	v_mfma_f32_16x16x32_bf16 v[12:15], v[128:131], v[204:207], v[12:15]
	v_mfma_f32_16x16x32_bf16 v[8:11], v[164:167], v[204:207], v[8:11]
	v_mfma_f32_16x16x32_bf16 v[60:63], v[132:135], v[184:187], v[60:63]
	v_mfma_f32_16x16x32_bf16 v[56:59], v[176:179], v[184:187], v[56:59]
	v_mfma_f32_16x16x32_bf16 v[44:47], v[132:135], v[192:195], v[44:47]
	v_mfma_f32_16x16x32_bf16 v[40:43], v[176:179], v[192:195], v[40:43]
	v_mfma_f32_16x16x32_bf16 v[28:31], v[132:135], v[200:203], v[28:31]
	v_mfma_f32_16x16x32_bf16 v[24:27], v[176:179], v[200:203], v[24:27]
	v_mfma_f32_16x16x32_bf16 v[12:15], v[132:135], v[208:211], v[12:15]
	v_mfma_f32_16x16x32_bf16 v[8:11], v[176:179], v[208:211], v[8:11]
	s_setprio 0
	s_barrier
	s_add_u32 s40, s8, 0x40000
	s_addc_u32 s41, s9, 0
	s_add_i32 s39, s59, s48
	v_lshl_add_u64 v[128:129], s[40:41], 0, v[138:139]
	s_mov_b32 m0, s39
	s_nop 0
	global_load_lds_dwordx4 v[128:129], off
	v_lshl_add_u64 v[128:129], s[40:41], 0, v[136:137]
	s_add_i32 m0, s39, 0x2000
	s_nop 0
	global_load_lds_dwordx4 v[128:129], off
	s_waitcnt vmcnt(6)
	s_barrier
	s_setprio 1
	v_mfma_f32_16x16x32_bf16 v[52:55], v[212:215], v[180:183], v[52:55]
	v_mfma_f32_16x16x32_bf16 v[48:51], v[220:223], v[180:183], v[48:51]
	v_mfma_f32_16x16x32_bf16 v[36:39], v[212:215], v[188:191], v[36:39]
	v_mfma_f32_16x16x32_bf16 v[32:35], v[220:223], v[188:191], v[32:35]
	v_mfma_f32_16x16x32_bf16 v[20:23], v[212:215], v[196:199], v[20:23]
	v_mfma_f32_16x16x32_bf16 v[16:19], v[220:223], v[196:199], v[16:19]
	v_mfma_f32_16x16x32_bf16 v[4:7], v[212:215], v[204:207], v[4:7]
	v_mfma_f32_16x16x32_bf16 v[0:3], v[220:223], v[204:207], v[0:3]
	v_mfma_f32_16x16x32_bf16 v[52:55], v[216:219], v[184:187], v[52:55]
	v_mfma_f32_16x16x32_bf16 v[48:51], v[224:227], v[184:187], v[48:51]
	v_mfma_f32_16x16x32_bf16 v[36:39], v[216:219], v[192:195], v[36:39]
	v_mfma_f32_16x16x32_bf16 v[32:35], v[224:227], v[192:195], v[32:35]
	v_mfma_f32_16x16x32_bf16 v[20:23], v[216:219], v[200:203], v[20:23]
	v_mfma_f32_16x16x32_bf16 v[16:19], v[224:227], v[200:203], v[16:19]
	v_mfma_f32_16x16x32_bf16 v[4:7], v[216:219], v[208:211], v[4:7]
	v_mfma_f32_16x16x32_bf16 v[0:3], v[224:227], v[208:211], v[0:3]
	s_setprio 0
	s_add_i32 s39, 0, 0x18000
	v_add_u32_e32 v176, s39, v149
	s_barrier
	ds_read_b128 v[128:131], v176
	ds_read_b128 v[132:135], v176 offset:1024
	ds_read_b128 v[164:167], v176 offset:2048
	ds_read_b128 v[176:179], v176 offset:3072
	s_add_u32 s10, s10, 0x40000
	s_addc_u32 s11, s11, 0
	s_mov_b32 m0, s51
	v_lshl_add_u64 v[212:213], s[10:11], 0, v[138:139]
	ds_read_b128 v[180:183], v171 offset:32768
	ds_read_b128 v[184:187], v171 offset:33792
	ds_read_b128 v[188:191], v171 offset:34816
	ds_read_b128 v[192:195], v171 offset:35840
	ds_read_b128 v[196:199], v171 offset:36864
	ds_read_b128 v[200:203], v171 offset:37888
	ds_read_b128 v[204:207], v171 offset:38912
	ds_read_b128 v[208:211], v171 offset:39936
	global_load_lds_dwordx4 v[212:213], off
	v_lshl_add_u64 v[212:213], s[10:11], 0, v[136:137]
	s_mov_b32 m0, s52
	s_nop 0
	global_load_lds_dwordx4 v[212:213], off
	s_waitcnt lgkmcnt(8)
	s_barrier
	s_waitcnt lgkmcnt(0)
	s_setprio 1
	s_waitcnt lgkmcnt(0)
	v_mfma_f32_16x16x32_bf16 v[124:127], v[128:131], v[180:183], v[124:127]
	v_mfma_f32_16x16x32_bf16 v[120:123], v[164:167], v[180:183], v[120:123]
	v_mfma_f32_16x16x32_bf16 v[108:111], v[128:131], v[188:191], v[108:111]
	v_mfma_f32_16x16x32_bf16 v[104:107], v[164:167], v[188:191], v[104:107]
	v_mfma_f32_16x16x32_bf16 v[92:95], v[128:131], v[196:199], v[92:95]
	v_mfma_f32_16x16x32_bf16 v[88:91], v[164:167], v[196:199], v[88:91]
	v_mfma_f32_16x16x32_bf16 v[76:79], v[128:131], v[204:207], v[76:79]
	v_mfma_f32_16x16x32_bf16 v[72:75], v[164:167], v[204:207], v[72:75]
	v_mfma_f32_16x16x32_bf16 v[124:127], v[132:135], v[184:187], v[124:127]
	v_mfma_f32_16x16x32_bf16 v[120:123], v[176:179], v[184:187], v[120:123]
	v_mfma_f32_16x16x32_bf16 v[108:111], v[132:135], v[192:195], v[108:111]
	v_mfma_f32_16x16x32_bf16 v[104:107], v[176:179], v[192:195], v[104:107]
	v_mfma_f32_16x16x32_bf16 v[92:95], v[132:135], v[200:203], v[92:95]
	v_mfma_f32_16x16x32_bf16 v[88:91], v[176:179], v[200:203], v[88:91]
	v_mfma_f32_16x16x32_bf16 v[76:79], v[132:135], v[208:211], v[76:79]
	v_mfma_f32_16x16x32_bf16 v[72:75], v[176:179], v[208:211], v[72:75]
	s_setprio 0
	s_barrier
	s_add_i32 s10, 0, 0x1c000
	s_add_i32 s11, s39, s48
	v_add_u32_e32 v224, s10, v149
	v_lshl_add_u64 v[168:169], v[168:169], 0, s[16:17]
	s_mov_b32 m0, s11
	ds_read_b128 v[212:215], v224
	ds_read_b128 v[216:219], v224 offset:1024
	ds_read_b128 v[220:223], v224 offset:2048
	ds_read_b128 v[224:227], v224 offset:3072
	global_load_lds_dwordx4 v[168:169], off
	v_lshl_add_u64 v[168:169], v[228:229], 0, s[16:17]
	s_add_i32 m0, s11, 0x2000
	s_nop 0
	global_load_lds_dwordx4 v[168:169], off
	s_barrier
	s_waitcnt lgkmcnt(0)
	s_setprio 1
	s_waitcnt lgkmcnt(0)
	v_mfma_f32_16x16x32_bf16 v[116:119], v[212:215], v[180:183], v[116:119]
	v_mfma_f32_16x16x32_bf16 v[112:115], v[220:223], v[180:183], v[112:115]
	v_mfma_f32_16x16x32_bf16 v[100:103], v[212:215], v[188:191], v[100:103]
	v_mfma_f32_16x16x32_bf16 v[96:99], v[220:223], v[188:191], v[96:99]
	v_mfma_f32_16x16x32_bf16 v[84:87], v[212:215], v[196:199], v[84:87]
	v_mfma_f32_16x16x32_bf16 v[80:83], v[220:223], v[196:199], v[80:83]
	v_mfma_f32_16x16x32_bf16 v[68:71], v[212:215], v[204:207], v[68:71]
	v_mfma_f32_16x16x32_bf16 v[64:67], v[220:223], v[204:207], v[64:67]
	v_mfma_f32_16x16x32_bf16 v[116:119], v[216:219], v[184:187], v[116:119]
	v_mfma_f32_16x16x32_bf16 v[112:115], v[224:227], v[184:187], v[112:115]
	v_mfma_f32_16x16x32_bf16 v[100:103], v[216:219], v[192:195], v[100:103]
	v_mfma_f32_16x16x32_bf16 v[96:99], v[224:227], v[192:195], v[96:99]
	v_mfma_f32_16x16x32_bf16 v[84:87], v[216:219], v[200:203], v[84:87]
	v_mfma_f32_16x16x32_bf16 v[80:83], v[224:227], v[200:203], v[80:83]
	v_mfma_f32_16x16x32_bf16 v[68:71], v[216:219], v[208:211], v[68:71]
	v_mfma_f32_16x16x32_bf16 v[64:67], v[224:227], v[208:211], v[64:67]
	s_setprio 0
	s_mov_b32 m0, s56
	v_lshl_add_u64 v[168:169], v[230:231], 0, s[16:17]
	s_barrier
	ds_read_b128 v[180:183], v171 offset:49152
	ds_read_b128 v[184:187], v171 offset:50176
	ds_read_b128 v[188:191], v171 offset:51200
	ds_read_b128 v[192:195], v171 offset:52224
	ds_read_b128 v[196:199], v171 offset:53248
	ds_read_b128 v[200:203], v171 offset:54272
	ds_read_b128 v[204:207], v171 offset:55296
	ds_read_b128 v[208:211], v171 offset:56320
	global_load_lds_dwordx4 v[168:169], off
	v_lshl_add_u64 v[168:169], v[232:233], 0, s[16:17]
	s_mov_b32 m0, s57
	s_nop 0
	global_load_lds_dwordx4 v[168:169], off
	s_barrier
	s_waitcnt lgkmcnt(0)
	s_setprio 1
	s_waitcnt lgkmcnt(0)
	v_mfma_f32_16x16x32_bf16 v[60:63], v[128:131], v[180:183], v[60:63]
	v_mfma_f32_16x16x32_bf16 v[56:59], v[164:167], v[180:183], v[56:59]
	v_mfma_f32_16x16x32_bf16 v[44:47], v[128:131], v[188:191], v[44:47]
	v_mfma_f32_16x16x32_bf16 v[40:43], v[164:167], v[188:191], v[40:43]
	v_mfma_f32_16x16x32_bf16 v[28:31], v[128:131], v[196:199], v[28:31]
	v_mfma_f32_16x16x32_bf16 v[24:27], v[164:167], v[196:199], v[24:27]
	v_mfma_f32_16x16x32_bf16 v[12:15], v[128:131], v[204:207], v[12:15]
	v_mfma_f32_16x16x32_bf16 v[8:11], v[164:167], v[204:207], v[8:11]
	v_mfma_f32_16x16x32_bf16 v[60:63], v[132:135], v[184:187], v[60:63]
	v_mfma_f32_16x16x32_bf16 v[56:59], v[176:179], v[184:187], v[56:59]
	v_mfma_f32_16x16x32_bf16 v[44:47], v[132:135], v[192:195], v[44:47]
	v_mfma_f32_16x16x32_bf16 v[40:43], v[176:179], v[192:195], v[40:43]
	v_mfma_f32_16x16x32_bf16 v[28:31], v[132:135], v[200:203], v[28:31]
	v_mfma_f32_16x16x32_bf16 v[24:27], v[176:179], v[200:203], v[24:27]
	v_mfma_f32_16x16x32_bf16 v[12:15], v[132:135], v[208:211], v[12:15]
	v_mfma_f32_16x16x32_bf16 v[8:11], v[176:179], v[208:211], v[8:11]
	s_setprio 0
	s_barrier
	s_add_u32 s8, s8, 0x40080
	s_addc_u32 s9, s9, 0
	s_add_i32 s10, s10, s48
	v_lshl_add_u64 v[128:129], s[8:9], 0, v[138:139]
	s_mov_b32 m0, s10
	s_nop 0
	global_load_lds_dwordx4 v[128:129], off
	v_lshl_add_u64 v[128:129], s[8:9], 0, v[136:137]
	s_add_i32 m0, s10, 0x2000
	s_nop 0
	global_load_lds_dwordx4 v[128:129], off
	s_waitcnt vmcnt(6)
	s_barrier
	s_setprio 1
	v_mfma_f32_16x16x32_bf16 v[52:55], v[212:215], v[180:183], v[52:55]
	v_mfma_f32_16x16x32_bf16 v[48:51], v[220:223], v[180:183], v[48:51]
	v_mfma_f32_16x16x32_bf16 v[36:39], v[212:215], v[188:191], v[36:39]
	v_mfma_f32_16x16x32_bf16 v[32:35], v[220:223], v[188:191], v[32:35]
	v_mfma_f32_16x16x32_bf16 v[20:23], v[212:215], v[196:199], v[20:23]
	v_mfma_f32_16x16x32_bf16 v[16:19], v[220:223], v[196:199], v[16:19]
	v_mfma_f32_16x16x32_bf16 v[4:7], v[212:215], v[204:207], v[4:7]
	v_mfma_f32_16x16x32_bf16 v[0:3], v[220:223], v[204:207], v[0:3]
	v_mfma_f32_16x16x32_bf16 v[52:55], v[216:219], v[184:187], v[52:55]
	v_mfma_f32_16x16x32_bf16 v[48:51], v[224:227], v[184:187], v[48:51]
	v_mfma_f32_16x16x32_bf16 v[36:39], v[216:219], v[192:195], v[36:39]
	v_mfma_f32_16x16x32_bf16 v[32:35], v[224:227], v[192:195], v[32:35]
	v_mfma_f32_16x16x32_bf16 v[20:23], v[216:219], v[200:203], v[20:23]
	v_mfma_f32_16x16x32_bf16 v[16:19], v[224:227], v[200:203], v[16:19]
	v_mfma_f32_16x16x32_bf16 v[4:7], v[216:219], v[208:211], v[4:7]
	v_mfma_f32_16x16x32_bf16 v[0:3], v[224:227], v[208:211], v[0:3]
	s_setprio 0
	s_add_i32 s38, s38, 2
	s_add_u32 s35, s35, 0x100
	s_addc_u32 s36, s36, 0
	s_add_u32 s6, s6, 0x100
	s_addc_u32 s7, s7, 0
	s_cmp_gt_u32 s38, 13
	s_barrier
	s_cbranch_scc0 .LBB0_412
	v_mbcnt_lo_u32_b32 v237, -1, 0
	v_mbcnt_hi_u32_b32 v237, -1, v237
	v_bfe_i32 v237, v237, 4, 1
	v_and_b32_e32 v238, 24, v237
	v_mov_b32_e32 v239, 0
	s_lshl_b32 s36, s37, 1
	s_add_i32 s6, s36, 0xffffff80
	s_lshr_b32 s63, s6, 4
	s_lshl_b32 s6, s30, 8
	s_add_i32 s63, s63, 4
	s_ashr_i32 s64, s37, 4
	s_or_b32 s23, s6, s55
	s_and_b32 s6, s30, 0xfffffe
	s_cmp_eq_u32 s6, 6
	s_cselect_b64 s[34:35], -1, 0
	s_cmp_eq_u32 s30, 7
	s_cselect_b64 s[30:31], -1, 0
	s_lshl_b32 s6, s37, 8
	s_cmp_lt_i32 s37, 64
	s_movk_i32 s7, 0xf00
	s_cselect_b32 s7, s7, 0x700
	s_cselect_b32 s8, s64, s63
	s_cselect_b32 s25, s60, 0x800
	s_cselect_b32 s65, 12, 11
	s_and_b32 s66, s7, s6
	s_lshl_b32 s7, s8, 11
	s_lshl_b32 s6, s8, 12
	s_addk_i32 s7, 0x2000
	s_cmp_lt_i32 s8, 4
	s_cselect_b32 s6, s6, s7
	s_ashr_i32 s7, s6, 31
	s_lshl_b64 s[6:7], s[6:7], 10
	s_add_u32 s38, s53, s6
	s_addc_u32 s39, s54, s7
	s_ashr_i32 s37, s36, 31
	v_add_u32_e32 v176, s66, v142
	s_lshl_b64 s[40:41], s[36:37], 7
	v_mul_lo_u32 v130, v176, 56
	s_lshr_b32 s67, s25, 1
	v_lshl_add_u64 v[128:129], s[40:41], 0, v[142:143]
	v_ashrrev_i32_e32 v131, 31, v130
	v_lshl_add_u64 v[168:169], v[130:131], 3, s[14:15]
	v_mad_u64_u32 v[164:165], s[8:9], v128, s61, 0
	s_cmpk_gt_i32 s23, 0x1ff
	v_mad_i32_i24 v165, v129, s61, v165
	v_lshl_add_u64 v[128:129], v[168:169], 0, s[18:19]
	s_cselect_b64 s[10:11], -1, 0
	v_cmp_lt_i32_e64 s[6:7], s67, v176
	v_lshl_add_u64 v[166:167], v[128:129], 0, v[140:141]
	s_mov_b64 s[8:9], -1
	s_and_b64 vcc, exec, s[10:11]
	s_cbranch_vccz .LBB0_424
	s_cmpk_gt_u32 s23, 0x109f
	s_cbranch_scc1 .LBB0_423
	s_add_i32 s8, s23, 0xfffffe00
	s_cmpk_gt_u32 s8, 0x1ff
	s_mov_b64 s[42:43], -1
	s_cbranch_scc0 .LBB0_421
	s_add_i32 s9, s23, 0xfffff700
	s_cmpk_lt_u32 s9, 0x400
	s_cselect_b64 s[42:43], -1, 0
	s_or_b64 s[42:43], s[34:35], s[42:43]
	v_mov_b64_e32 v[134:135], v[126:127]
	v_mov_b64_e32 v[130:131], v[122:123]
	s_andn2_b64 vcc, exec, s[42:43]
	v_mov_b64_e32 v[132:133], v[124:125]
	v_mov_b64_e32 v[128:129], v[120:121]
	s_cbranch_vccnz .LBB0_420
	s_andn2_b64 vcc, exec, s[20:21]
	v_mov_b32_e32 v128, v124
	v_mov_b32_e32 v129, v125
	v_mov_b32_e32 v130, v126
	v_mov_b32_e32 v131, v127
	s_cbranch_vccnz .LBB0_419
	v_and_b32_e32 v129, 64, v173
	v_xor_b32_e32 v128, 32, v173
	v_add_u32_e32 v129, 64, v129
	v_cmp_lt_i32_e32 vcc, v128, v129
	v_mov_b32_e32 v129, v141
	s_nop 0
	v_cndmask_b32_e32 v128, v173, v128, vcc
	v_lshlrev_b32_e32 v177, 2, v128
	v_lshlrev_b32_e32 v128, 3, v146
	v_lshl_add_u64 v[132:133], v[168:169], 0, v[128:129]
	s_waitcnt vmcnt(0)
	global_load_dwordx4 v[128:131], v[132:133], off offset:128
	ds_bpermute_b32 v134, v177, v124
	ds_bpermute_b32 v135, v177, v125
	s_waitcnt vmcnt(0) lgkmcnt(0)
	v_mov_b32_e32 v179, v130
	v_mov_b32_e32 v130, v129
	v_mov_b32_e32 v178, v128
	v_pk_mul_f32 v[128:129], v[130:131], v[134:135]
	global_load_dwordx4 v[130:133], v[132:133], off offset:144
	ds_bpermute_b32 v134, v177, v126
	ds_bpermute_b32 v135, v177, v127
	v_cndmask_b32_e64 v129, v129, -v129, s[0:1]
	v_cndmask_b32_e64 v128, v128, -v128, s[0:1]
	v_pk_fma_f32 v[128:129], v[124:125], v[178:179], v[128:129]
	s_waitcnt vmcnt(0) lgkmcnt(0)
	v_mov_b32_e32 v179, v132
	v_mov_b32_e32 v132, v131
	v_mov_b32_e32 v178, v130
	v_pk_mul_f32 v[130:131], v[132:133], v[134:135]
	s_nop 0
	v_cndmask_b32_e64 v131, v131, -v131, s[0:1]
	v_cndmask_b32_e64 v130, v130, -v130, s[0:1]
	v_pk_fma_f32 v[130:131], v[126:127], v[178:179], v[130:131]

.LBB0_420:
	v_cvt_pk_bf16_f32 v132, v132, v133
	v_cvt_pk_bf16_f32 v133, v134, v135
	v_lshl_add_u64 v[134:135], v[164:165], 1, s[12:13]
	s_mov_b32 s9, s19
	v_lshl_add_u64 v[134:135], s[8:9], 1, v[134:135]
	v_lshlrev_b32_e32 v178, 1, v144
	v_mov_b32_e32 v179, v141
	v_lshl_add_u64 v[134:135], v[134:135], 0, v[178:179]
	v_cvt_pk_bf16_f32 v128, v128, v129
	v_cvt_pk_bf16_f32 v129, v130, v131
	s_mov_b64 s[42:43], 0
	s_waitcnt vmcnt(0)
	v_mov_b32_e32 v244, v132
	v_mov_b32_e32 v245, v133
	v_bfi_b32 v246, v237, v244, v128
	v_bfi_b32 v247, v237, v245, v129
	ds_swizzle_b32 v250, v246 offset:0x401f
	ds_swizzle_b32 v251, v247 offset:0x401f
	v_lshl_add_u64 v[248:249], v[134:135], 0, v[238:239]
	s_waitcnt lgkmcnt(0)
	v_bfi_b32 v240, v237, v250, v244
	v_bfi_b32 v241, v237, v251, v245
	v_bfi_b32 v242, v237, v128, v250
	v_bfi_b32 v243, v237, v129, v251
	global_store_dwordx4 v[248:249], v[240:243], off
	s_nop 1

.LBB0_437:
	v_cvt_pk_bf16_f32 v122, v122, v123
	v_cvt_pk_bf16_f32 v123, v120, v121
	v_lshl_add_u64 v[120:121], v[164:165], 1, s[12:13]
	s_mov_b32 s7, s19
	v_lshl_add_u64 v[120:121], s[6:7], 1, v[120:121]
	v_lshlrev_b32_e32 v132, 1, v144
	v_mov_b32_e32 v133, v141
	v_lshl_add_u64 v[120:121], v[120:121], 0, v[132:133]
	s_waitcnt vmcnt(0)
	v_mov_b32_e32 v244, v122
	v_mov_b32_e32 v245, v123
	v_cvt_pk_bf16_f32 v122, v126, v127
	v_cvt_pk_bf16_f32 v123, v124, v125
	s_mov_b64 s[8:9], 0
	v_bfi_b32 v246, v237, v244, v122
	v_bfi_b32 v247, v237, v245, v123
	ds_swizzle_b32 v250, v246 offset:0x401f
	ds_swizzle_b32 v251, v247 offset:0x401f
	v_lshl_add_u64 v[248:249], v[120:121], 0, v[238:239]
	s_waitcnt lgkmcnt(0)
	v_bfi_b32 v240, v237, v250, v244
	v_bfi_b32 v241, v237, v251, v245
	v_bfi_b32 v242, v237, v122, v250
	v_bfi_b32 v243, v237, v123, v251
	global_store_dwordx4 v[248:249], v[240:243], off
	s_nop 1

.LBB0_450:
	v_cvt_pk_bf16_f32 v116, v116, v117
	v_cvt_pk_bf16_f32 v117, v118, v119
	v_lshl_add_u64 v[118:119], v[122:123], 1, s[12:13]
	s_mov_b32 s11, s19
	v_lshl_add_u64 v[118:119], s[10:11], 1, v[118:119]
	v_lshlrev_b32_e32 v130, 1, v144
	v_mov_b32_e32 v131, v141
	v_lshl_add_u64 v[118:119], v[118:119], 0, v[130:131]
	v_cvt_pk_bf16_f32 v112, v112, v113
	v_cvt_pk_bf16_f32 v113, v114, v115
	s_mov_b64 s[44:45], 0
	s_waitcnt vmcnt(0)
	v_mov_b32_e32 v244, v116
	v_mov_b32_e32 v245, v117
	v_bfi_b32 v246, v237, v244, v112
	v_bfi_b32 v247, v237, v245, v113
	ds_swizzle_b32 v250, v246 offset:0x401f
	ds_swizzle_b32 v251, v247 offset:0x401f
	v_lshl_add_u64 v[248:249], v[118:119], 0, v[238:239]
	s_waitcnt lgkmcnt(0)
	v_bfi_b32 v240, v237, v250, v244
	v_bfi_b32 v241, v237, v251, v245
	v_bfi_b32 v242, v237, v112, v250
	v_bfi_b32 v243, v237, v113, v251
	global_store_dwordx4 v[248:249], v[240:243], off
	s_nop 1

.LBB0_467:
	v_cvt_pk_bf16_f32 v106, v106, v107
	v_cvt_pk_bf16_f32 v107, v104, v105
	v_lshl_add_u64 v[104:105], v[122:123], 1, s[12:13]
	s_mov_b32 s11, s19
	v_lshl_add_u64 v[104:105], s[10:11], 1, v[104:105]
	v_lshlrev_b32_e32 v114, 1, v144
	v_mov_b32_e32 v115, v141
	v_lshl_add_u64 v[104:105], v[104:105], 0, v[114:115]
	s_waitcnt vmcnt(0)
	v_mov_b32_e32 v244, v106
	v_mov_b32_e32 v245, v107
	v_cvt_pk_bf16_f32 v106, v110, v111
	v_cvt_pk_bf16_f32 v107, v108, v109
	s_mov_b64 s[42:43], 0
	v_bfi_b32 v246, v237, v244, v106
	v_bfi_b32 v247, v237, v245, v107
	ds_swizzle_b32 v250, v246 offset:0x401f
	ds_swizzle_b32 v251, v247 offset:0x401f
	v_lshl_add_u64 v[248:249], v[104:105], 0, v[238:239]
	s_waitcnt lgkmcnt(0)
	v_bfi_b32 v240, v237, v250, v244
	v_bfi_b32 v241, v237, v251, v245
	v_bfi_b32 v242, v237, v106, v250
	v_bfi_b32 v243, v237, v107, v251
	global_store_dwordx4 v[248:249], v[240:243], off
	s_nop 1

.LBB0_480:
	v_cvt_pk_bf16_f32 v100, v100, v101
	v_cvt_pk_bf16_f32 v101, v102, v103
	v_lshl_add_u64 v[102:103], v[104:105], 1, s[12:13]
	s_mov_b32 s43, s19
	v_lshl_add_u64 v[102:103], s[42:43], 1, v[102:103]
	v_lshlrev_b32_e32 v112, 1, v144
	v_mov_b32_e32 v113, v141
	v_lshl_add_u64 v[102:103], v[102:103], 0, v[112:113]
	v_cvt_pk_bf16_f32 v96, v96, v97
	v_cvt_pk_bf16_f32 v97, v98, v99
	s_mov_b64 s[44:45], 0
	s_waitcnt vmcnt(0)
	v_mov_b32_e32 v244, v100
	v_mov_b32_e32 v245, v101
	v_bfi_b32 v246, v237, v244, v96
	v_bfi_b32 v247, v237, v245, v97
	ds_swizzle_b32 v250, v246 offset:0x401f
	ds_swizzle_b32 v251, v247 offset:0x401f
	v_lshl_add_u64 v[248:249], v[102:103], 0, v[238:239]
	s_waitcnt lgkmcnt(0)
	v_bfi_b32 v240, v237, v250, v244
	v_bfi_b32 v241, v237, v251, v245
	v_bfi_b32 v242, v237, v96, v250
	v_bfi_b32 v243, v237, v97, v251
	global_store_dwordx4 v[248:249], v[240:243], off
	s_nop 1

.LBB0_495:
	v_cvt_pk_bf16_f32 v84, v84, v85
	v_cvt_pk_bf16_f32 v85, v86, v87
	v_lshl_add_u64 v[86:87], v[88:89], 1, s[12:13]
	s_mov_b32 s41, s19
	v_lshl_add_u64 v[86:87], s[40:41], 1, v[86:87]
	v_lshlrev_b32_e32 v96, 1, v144
	v_mov_b32_e32 v97, v141
	v_lshl_add_u64 v[86:87], v[86:87], 0, v[96:97]
	v_cvt_pk_bf16_f32 v80, v80, v81
	v_cvt_pk_bf16_f32 v81, v82, v83
	s_mov_b64 s[42:43], 0
	s_waitcnt vmcnt(0)
	v_mov_b32_e32 v244, v84
	v_mov_b32_e32 v245, v85
	v_bfi_b32 v246, v237, v244, v80
	v_bfi_b32 v247, v237, v245, v81
	ds_swizzle_b32 v250, v246 offset:0x401f
	ds_swizzle_b32 v251, v247 offset:0x401f
	v_lshl_add_u64 v[248:249], v[86:87], 0, v[238:239]
	s_waitcnt lgkmcnt(0)
	v_bfi_b32 v240, v237, v250, v244
	v_bfi_b32 v241, v237, v251, v245
	v_bfi_b32 v242, v237, v80, v250
	v_bfi_b32 v243, v237, v81, v251
	global_store_dwordx4 v[248:249], v[240:243], off
	s_nop 1

.LBB0_510:
	v_cvt_pk_bf16_f32 v68, v68, v69
	v_cvt_pk_bf16_f32 v69, v70, v71
	v_lshl_add_u64 v[70:71], v[72:73], 1, s[12:13]
	s_mov_b32 s41, s19
	v_lshl_add_u64 v[70:71], s[40:41], 1, v[70:71]
	v_lshlrev_b32_e32 v80, 1, v144
	v_mov_b32_e32 v81, v141
	v_lshl_add_u64 v[70:71], v[70:71], 0, v[80:81]
	v_cvt_pk_bf16_f32 v64, v64, v65
	v_cvt_pk_bf16_f32 v65, v66, v67
	s_mov_b64 s[42:43], 0
	s_waitcnt vmcnt(0)
	v_mov_b32_e32 v244, v68
	v_mov_b32_e32 v245, v69
	v_bfi_b32 v246, v237, v244, v64
	v_bfi_b32 v247, v237, v245, v65
	ds_swizzle_b32 v250, v246 offset:0x401f
	ds_swizzle_b32 v251, v247 offset:0x401f
	v_lshl_add_u64 v[248:249], v[70:71], 0, v[238:239]
	s_waitcnt lgkmcnt(0)
	v_bfi_b32 v240, v237, v250, v244
	v_bfi_b32 v241, v237, v251, v245
	v_bfi_b32 v242, v237, v64, v250
	v_bfi_b32 v243, v237, v65, v251
	global_store_dwordx4 v[248:249], v[240:243], off
	s_nop 1

.LBB0_525:
	v_cvt_pk_bf16_f32 v52, v52, v53
	v_cvt_pk_bf16_f32 v53, v54, v55
	v_lshl_add_u64 v[54:55], v[56:57], 1, s[12:13]
	s_mov_b32 s41, s19
	v_lshl_add_u64 v[54:55], s[40:41], 1, v[54:55]
	v_lshlrev_b32_e32 v64, 1, v144
	v_mov_b32_e32 v65, v141
	v_lshl_add_u64 v[54:55], v[54:55], 0, v[64:65]
	v_cvt_pk_bf16_f32 v48, v48, v49
	v_cvt_pk_bf16_f32 v49, v50, v51
	s_mov_b64 s[42:43], 0
	s_waitcnt vmcnt(0)
	v_mov_b32_e32 v244, v52
	v_mov_b32_e32 v245, v53
	v_bfi_b32 v246, v237, v244, v48
	v_bfi_b32 v247, v237, v245, v49
	ds_swizzle_b32 v250, v246 offset:0x401f
	ds_swizzle_b32 v251, v247 offset:0x401f
	v_lshl_add_u64 v[248:249], v[54:55], 0, v[238:239]
	s_waitcnt lgkmcnt(0)
	v_bfi_b32 v240, v237, v250, v244
	v_bfi_b32 v241, v237, v251, v245
	v_bfi_b32 v242, v237, v48, v250
	v_bfi_b32 v243, v237, v49, v251
	global_store_dwordx4 v[248:249], v[240:243], off
	s_nop 1

.LBB0_540:
	v_cvt_pk_bf16_f32 v36, v36, v37
	v_cvt_pk_bf16_f32 v37, v38, v39
	v_lshl_add_u64 v[38:39], v[40:41], 1, s[12:13]
	s_mov_b32 s41, s19
	v_lshl_add_u64 v[38:39], s[40:41], 1, v[38:39]
	v_lshlrev_b32_e32 v48, 1, v144
	v_mov_b32_e32 v49, v141
	v_lshl_add_u64 v[38:39], v[38:39], 0, v[48:49]
	v_cvt_pk_bf16_f32 v32, v32, v33
	v_cvt_pk_bf16_f32 v33, v34, v35
	s_mov_b64 s[42:43], 0
	s_waitcnt vmcnt(0)
	v_mov_b32_e32 v244, v36
	v_mov_b32_e32 v245, v37
	v_bfi_b32 v246, v237, v244, v32
	v_bfi_b32 v247, v237, v245, v33
	ds_swizzle_b32 v250, v246 offset:0x401f
	ds_swizzle_b32 v251, v247 offset:0x401f
	v_lshl_add_u64 v[248:249], v[38:39], 0, v[238:239]
	s_waitcnt lgkmcnt(0)
	v_bfi_b32 v240, v237, v250, v244
	v_bfi_b32 v241, v237, v251, v245
	v_bfi_b32 v242, v237, v32, v250
	v_bfi_b32 v243, v237, v33, v251
	global_store_dwordx4 v[248:249], v[240:243], off
	s_nop 1

.LBB0_555:
	v_cvt_pk_bf16_f32 v20, v20, v21
	v_cvt_pk_bf16_f32 v21, v22, v23
	v_lshl_add_u64 v[22:23], v[24:25], 1, s[12:13]
	s_mov_b32 s7, s19
	v_lshl_add_u64 v[22:23], s[6:7], 1, v[22:23]
	v_lshlrev_b32_e32 v32, 1, v144
	v_mov_b32_e32 v33, v141
	v_lshl_add_u64 v[22:23], v[22:23], 0, v[32:33]
	v_cvt_pk_bf16_f32 v16, v16, v17
	v_cvt_pk_bf16_f32 v17, v18, v19
	s_mov_b64 s[38:39], 0
	s_waitcnt vmcnt(0)
	v_mov_b32_e32 v244, v20
	v_mov_b32_e32 v245, v21
	v_bfi_b32 v246, v237, v244, v16
	v_bfi_b32 v247, v237, v245, v17
	ds_swizzle_b32 v250, v246 offset:0x401f
	ds_swizzle_b32 v251, v247 offset:0x401f
	v_lshl_add_u64 v[248:249], v[22:23], 0, v[238:239]
	s_waitcnt lgkmcnt(0)
	v_bfi_b32 v240, v237, v250, v244
	v_bfi_b32 v241, v237, v251, v245
	v_bfi_b32 v242, v237, v16, v250
	v_bfi_b32 v243, v237, v17, v251
	global_store_dwordx4 v[248:249], v[240:243], off
	s_nop 1

.LBB0_573:
	v_cvt_pk_bf16_f32 v90, v90, v91
	v_cvt_pk_bf16_f32 v91, v88, v89
	v_lshl_add_u64 v[88:89], v[104:105], 1, s[12:13]
	s_mov_b32 s11, s19
	v_lshl_add_u64 v[88:89], s[10:11], 1, v[88:89]
	v_lshlrev_b32_e32 v98, 1, v144
	v_mov_b32_e32 v99, v141
	v_lshl_add_u64 v[88:89], v[88:89], 0, v[98:99]
	s_waitcnt vmcnt(0)
	v_mov_b32_e32 v244, v90
	v_mov_b32_e32 v245, v91
	v_cvt_pk_bf16_f32 v90, v94, v95
	v_cvt_pk_bf16_f32 v91, v92, v93
	s_mov_b64 s[42:43], 0
	v_bfi_b32 v246, v237, v244, v90
	v_bfi_b32 v247, v237, v245, v91
	ds_swizzle_b32 v250, v246 offset:0x401f
	ds_swizzle_b32 v251, v247 offset:0x401f
	v_lshl_add_u64 v[248:249], v[88:89], 0, v[238:239]
	s_waitcnt lgkmcnt(0)
	v_bfi_b32 v240, v237, v250, v244
	v_bfi_b32 v241, v237, v251, v245
	v_bfi_b32 v242, v237, v90, v250
	v_bfi_b32 v243, v237, v91, v251
	global_store_dwordx4 v[248:249], v[240:243], off
	s_nop 1

.LBB0_588:
	v_cvt_pk_bf16_f32 v74, v74, v75
	v_cvt_pk_bf16_f32 v75, v72, v73
	v_lshl_add_u64 v[72:73], v[88:89], 1, s[12:13]
	s_mov_b32 s11, s19
	v_lshl_add_u64 v[72:73], s[10:11], 1, v[72:73]
	v_lshlrev_b32_e32 v82, 1, v144
	v_mov_b32_e32 v83, v141
	v_lshl_add_u64 v[72:73], v[72:73], 0, v[82:83]
	s_waitcnt vmcnt(0)
	v_mov_b32_e32 v244, v74
	v_mov_b32_e32 v245, v75
	v_cvt_pk_bf16_f32 v74, v78, v79
	v_cvt_pk_bf16_f32 v75, v76, v77
	s_mov_b64 s[38:39], 0
	v_bfi_b32 v246, v237, v244, v74
	v_bfi_b32 v247, v237, v245, v75
	ds_swizzle_b32 v250, v246 offset:0x401f
	ds_swizzle_b32 v251, v247 offset:0x401f
	v_lshl_add_u64 v[248:249], v[72:73], 0, v[238:239]
	s_waitcnt lgkmcnt(0)
	v_bfi_b32 v240, v237, v250, v244
	v_bfi_b32 v241, v237, v251, v245
	v_bfi_b32 v242, v237, v74, v250
	v_bfi_b32 v243, v237, v75, v251
	global_store_dwordx4 v[248:249], v[240:243], off
	s_nop 1

.LBB0_603:
	v_cvt_pk_bf16_f32 v58, v58, v59
	v_cvt_pk_bf16_f32 v59, v56, v57
	v_lshl_add_u64 v[56:57], v[72:73], 1, s[12:13]
	s_mov_b32 s11, s19
	v_lshl_add_u64 v[56:57], s[10:11], 1, v[56:57]
	v_lshlrev_b32_e32 v66, 1, v144
	v_mov_b32_e32 v67, v141
	v_lshl_add_u64 v[56:57], v[56:57], 0, v[66:67]
	s_waitcnt vmcnt(0)
	v_mov_b32_e32 v244, v58
	v_mov_b32_e32 v245, v59
	v_cvt_pk_bf16_f32 v58, v62, v63
	v_cvt_pk_bf16_f32 v59, v60, v61
	s_mov_b64 s[40:41], 0
	v_bfi_b32 v246, v237, v244, v58
	v_bfi_b32 v247, v237, v245, v59
	ds_swizzle_b32 v250, v246 offset:0x401f
	ds_swizzle_b32 v251, v247 offset:0x401f
	v_lshl_add_u64 v[248:249], v[56:57], 0, v[238:239]
	s_waitcnt lgkmcnt(0)
	v_bfi_b32 v240, v237, v250, v244
	v_bfi_b32 v241, v237, v251, v245
	v_bfi_b32 v242, v237, v58, v250
	v_bfi_b32 v243, v237, v59, v251
	global_store_dwordx4 v[248:249], v[240:243], off
	s_nop 1

.LBB0_618:
	v_cvt_pk_bf16_f32 v42, v42, v43
	v_cvt_pk_bf16_f32 v43, v40, v41
	v_lshl_add_u64 v[40:41], v[56:57], 1, s[12:13]
	s_mov_b32 s11, s19
	v_lshl_add_u64 v[40:41], s[10:11], 1, v[40:41]
	v_lshlrev_b32_e32 v50, 1, v144
	v_mov_b32_e32 v51, v141
	v_lshl_add_u64 v[40:41], v[40:41], 0, v[50:51]
	s_waitcnt vmcnt(0)
	v_mov_b32_e32 v244, v42
	v_mov_b32_e32 v245, v43
	v_cvt_pk_bf16_f32 v42, v46, v47
	v_cvt_pk_bf16_f32 v43, v44, v45
	s_mov_b64 s[40:41], 0
	v_bfi_b32 v246, v237, v244, v42
	v_bfi_b32 v247, v237, v245, v43
	ds_swizzle_b32 v250, v246 offset:0x401f
	ds_swizzle_b32 v251, v247 offset:0x401f
	v_lshl_add_u64 v[248:249], v[40:41], 0, v[238:239]
	s_waitcnt lgkmcnt(0)
	v_bfi_b32 v240, v237, v250, v244
	v_bfi_b32 v241, v237, v251, v245
	v_bfi_b32 v242, v237, v42, v250
	v_bfi_b32 v243, v237, v43, v251
	global_store_dwordx4 v[248:249], v[240:243], off
	s_nop 1

.LBB0_633:
	v_cvt_pk_bf16_f32 v26, v26, v27
	v_cvt_pk_bf16_f32 v27, v24, v25
	v_lshl_add_u64 v[24:25], v[40:41], 1, s[12:13]
	s_mov_b32 s11, s19
	v_lshl_add_u64 v[24:25], s[10:11], 1, v[24:25]
	v_lshlrev_b32_e32 v34, 1, v144
	v_mov_b32_e32 v35, v141
	v_lshl_add_u64 v[24:25], v[24:25], 0, v[34:35]
	s_waitcnt vmcnt(0)
	v_mov_b32_e32 v244, v26
	v_mov_b32_e32 v245, v27
	v_cvt_pk_bf16_f32 v26, v30, v31
	v_cvt_pk_bf16_f32 v27, v28, v29
	s_mov_b64 s[40:41], 0
	v_bfi_b32 v246, v237, v244, v26
	v_bfi_b32 v247, v237, v245, v27
	ds_swizzle_b32 v250, v246 offset:0x401f
	ds_swizzle_b32 v251, v247 offset:0x401f
	v_lshl_add_u64 v[248:249], v[24:25], 0, v[238:239]
	s_waitcnt lgkmcnt(0)
	v_bfi_b32 v240, v237, v250, v244
	v_bfi_b32 v241, v237, v251, v245
	v_bfi_b32 v242, v237, v26, v250
	v_bfi_b32 v243, v237, v27, v251
	global_store_dwordx4 v[248:249], v[240:243], off
	s_nop 1

.LBB0_648:
	v_cvt_pk_bf16_f32 v12, v12, v13
	v_cvt_pk_bf16_f32 v13, v10, v11
	v_lshl_add_u64 v[10:11], v[24:25], 1, s[12:13]
	s_mov_b32 s7, s19
	v_lshl_add_u64 v[10:11], s[6:7], 1, v[10:11]
	v_lshlrev_b32_e32 v18, 1, v144
	v_mov_b32_e32 v19, v141
	v_lshl_add_u64 v[10:11], v[10:11], 0, v[18:19]
	s_waitcnt vmcnt(0)
	v_mov_b32_e32 v244, v12
	v_mov_b32_e32 v245, v13
	v_cvt_pk_bf16_f32 v12, v14, v15
	v_cvt_pk_bf16_f32 v13, v8, v9
	s_mov_b64 s[8:9], 0
	v_bfi_b32 v246, v237, v244, v12
	v_bfi_b32 v247, v237, v245, v13
	ds_swizzle_b32 v250, v246 offset:0x401f
	ds_swizzle_b32 v251, v247 offset:0x401f
	v_lshl_add_u64 v[248:249], v[10:11], 0, v[238:239]
	s_waitcnt lgkmcnt(0)
	v_bfi_b32 v240, v237, v250, v244
	v_bfi_b32 v241, v237, v251, v245
	v_bfi_b32 v242, v237, v12, v250
	v_bfi_b32 v243, v237, v13, v251
	global_store_dwordx4 v[248:249], v[240:243], off
	s_nop 1

.LBB0_1407:
	ds_read_b128 v[128:131], v149
	ds_read_b128 v[132:135], v149 offset:1024
	ds_read_b128 v[164:167], v149 offset:2048
	ds_read_b128 v[176:179], v149 offset:3072
	s_add_u32 s12, s10, 0xfffc0080
	s_addc_u32 s13, s11, -1
	s_cmp_eq_u32 s36, 12
	s_cselect_b32 s15, s25, s13
	s_cselect_b32 s14, s30, s12
	s_cselect_b32 s13, s23, s35
	s_cselect_b32 s12, s31, s34
	v_lshl_add_u64 v[168:169], s[10:11], 0, v[158:159]
	s_add_i32 m0, s49, 0xc000
	ds_read_b128 v[180:183], v171
	ds_read_b128 v[184:187], v171 offset:1024
	ds_read_b128 v[188:191], v171 offset:2048
	ds_read_b128 v[192:195], v171 offset:3072
	ds_read_b128 v[196:199], v171 offset:4096
	ds_read_b128 v[200:203], v171 offset:5120
	ds_read_b128 v[204:207], v171 offset:6144
	ds_read_b128 v[208:211], v171 offset:7168
	global_load_lds_dwordx4 v[168:169], off
	v_lshl_add_u64 v[168:169], s[10:11], 0, v[156:157]
	s_add_i32 m0, s49, 0xe000
	s_nop 0
	global_load_lds_dwordx4 v[168:169], off
	s_waitcnt lgkmcnt(8)
	s_barrier
	s_waitcnt lgkmcnt(0)
	s_setprio 1
	s_waitcnt lgkmcnt(0)
	v_mfma_f32_16x16x32_bf16 v[124:127], v[128:131], v[180:183], v[124:127]
	v_mfma_f32_16x16x32_bf16 v[120:123], v[164:167], v[180:183], v[120:123]
	v_mfma_f32_16x16x32_bf16 v[108:111], v[128:131], v[188:191], v[108:111]
	v_mfma_f32_16x16x32_bf16 v[104:107], v[164:167], v[188:191], v[104:107]
	v_mfma_f32_16x16x32_bf16 v[92:95], v[128:131], v[196:199], v[92:95]
	v_mfma_f32_16x16x32_bf16 v[88:91], v[164:167], v[196:199], v[88:91]
	v_mfma_f32_16x16x32_bf16 v[76:79], v[128:131], v[204:207], v[76:79]
	v_mfma_f32_16x16x32_bf16 v[72:75], v[164:167], v[204:207], v[72:75]
	v_mfma_f32_16x16x32_bf16 v[124:127], v[132:135], v[184:187], v[124:127]
	v_mfma_f32_16x16x32_bf16 v[120:123], v[176:179], v[184:187], v[120:123]
	v_mfma_f32_16x16x32_bf16 v[108:111], v[132:135], v[192:195], v[108:111]
	v_mfma_f32_16x16x32_bf16 v[104:107], v[176:179], v[192:195], v[104:107]
	v_mfma_f32_16x16x32_bf16 v[92:95], v[132:135], v[200:203], v[92:95]
	v_mfma_f32_16x16x32_bf16 v[88:91], v[176:179], v[200:203], v[88:91]
	v_mfma_f32_16x16x32_bf16 v[76:79], v[132:135], v[208:211], v[76:79]
	v_mfma_f32_16x16x32_bf16 v[72:75], v[176:179], v[208:211], v[72:75]
	s_setprio 0
	s_barrier
	s_add_i32 s37, s58, s48
	v_lshl_add_u64 v[168:169], s[12:13], 0, v[138:139]
	s_mov_b32 m0, s37
	ds_read_b128 v[212:215], v172
	ds_read_b128 v[216:219], v172 offset:1024
	ds_read_b128 v[220:223], v172 offset:2048
	ds_read_b128 v[224:227], v172 offset:3072
	global_load_lds_dwordx4 v[168:169], off
	v_lshl_add_u64 v[228:229], s[12:13], 0, v[136:137]
	s_add_i32 m0, s37, 0x2000
	s_nop 0
	global_load_lds_dwordx4 v[228:229], off
	s_barrier
	s_waitcnt lgkmcnt(0)
	s_setprio 1
	s_waitcnt lgkmcnt(0)
	v_mfma_f32_16x16x32_bf16 v[116:119], v[212:215], v[180:183], v[116:119]
	v_mfma_f32_16x16x32_bf16 v[112:115], v[220:223], v[180:183], v[112:115]
	v_mfma_f32_16x16x32_bf16 v[100:103], v[212:215], v[188:191], v[100:103]
	v_mfma_f32_16x16x32_bf16 v[96:99], v[220:223], v[188:191], v[96:99]
	v_mfma_f32_16x16x32_bf16 v[84:87], v[212:215], v[196:199], v[84:87]
	v_mfma_f32_16x16x32_bf16 v[80:83], v[220:223], v[196:199], v[80:83]
	v_mfma_f32_16x16x32_bf16 v[68:71], v[212:215], v[204:207], v[68:71]
	v_mfma_f32_16x16x32_bf16 v[64:67], v[220:223], v[204:207], v[64:67]
	v_mfma_f32_16x16x32_bf16 v[116:119], v[216:219], v[184:187], v[116:119]
	v_mfma_f32_16x16x32_bf16 v[112:115], v[224:227], v[184:187], v[112:115]
	v_mfma_f32_16x16x32_bf16 v[100:103], v[216:219], v[192:195], v[100:103]
	v_mfma_f32_16x16x32_bf16 v[96:99], v[224:227], v[192:195], v[96:99]
	v_mfma_f32_16x16x32_bf16 v[84:87], v[216:219], v[200:203], v[84:87]
	v_mfma_f32_16x16x32_bf16 v[80:83], v[224:227], v[200:203], v[80:83]
	v_mfma_f32_16x16x32_bf16 v[68:71], v[216:219], v[208:211], v[68:71]
	v_mfma_f32_16x16x32_bf16 v[64:67], v[224:227], v[208:211], v[64:67]
	s_setprio 0
	s_mov_b32 m0, s49
	v_lshl_add_u64 v[230:231], s[14:15], 0, v[138:139]
	s_barrier
	ds_read_b128 v[180:183], v171 offset:16384
	ds_read_b128 v[184:187], v171 offset:17408
	ds_read_b128 v[188:191], v171 offset:18432
	ds_read_b128 v[192:195], v171 offset:19456
	ds_read_b128 v[196:199], v171 offset:20480
	ds_read_b128 v[200:203], v171 offset:21504
	ds_read_b128 v[204:207], v171 offset:22528
	ds_read_b128 v[208:211], v171 offset:23552
	global_load_lds_dwordx4 v[230:231], off
	v_lshl_add_u64 v[232:233], s[14:15], 0, v[136:137]
	s_mov_b32 m0, s50
	s_nop 0
	global_load_lds_dwordx4 v[232:233], off
	s_barrier
	s_waitcnt lgkmcnt(0)
	s_setprio 1
	s_waitcnt lgkmcnt(0)
	v_mfma_f32_16x16x32_bf16 v[60:63], v[128:131], v[180:183], v[60:63]
	v_mfma_f32_16x16x32_bf16 v[56:59], v[164:167], v[180:183], v[56:59]
	v_mfma_f32_16x16x32_bf16 v[44:47], v[128:131], v[188:191], v[44:47]
	v_mfma_f32_16x16x32_bf16 v[40:43], v[164:167], v[188:191], v[40:43]
	v_mfma_f32_16x16x32_bf16 v[28:31], v[128:131], v[196:199], v[28:31]
	v_mfma_f32_16x16x32_bf16 v[24:27], v[164:167], v[196:199], v[24:27]
	v_mfma_f32_16x16x32_bf16 v[12:15], v[128:131], v[204:207], v[12:15]
	v_mfma_f32_16x16x32_bf16 v[8:11], v[164:167], v[204:207], v[8:11]
	v_mfma_f32_16x16x32_bf16 v[60:63], v[132:135], v[184:187], v[60:63]
	v_mfma_f32_16x16x32_bf16 v[56:59], v[176:179], v[184:187], v[56:59]
	v_mfma_f32_16x16x32_bf16 v[44:47], v[132:135], v[192:195], v[44:47]
	v_mfma_f32_16x16x32_bf16 v[40:43], v[176:179], v[192:195], v[40:43]
	v_mfma_f32_16x16x32_bf16 v[28:31], v[132:135], v[200:203], v[28:31]
	v_mfma_f32_16x16x32_bf16 v[24:27], v[176:179], v[200:203], v[24:27]
	v_mfma_f32_16x16x32_bf16 v[12:15], v[132:135], v[208:211], v[12:15]
	v_mfma_f32_16x16x32_bf16 v[8:11], v[176:179], v[208:211], v[8:11]
	s_setprio 0
	s_barrier
	s_add_u32 s38, s12, 0x40000
	s_addc_u32 s39, s13, 0
	s_add_i32 s37, s59, s48
	v_lshl_add_u64 v[128:129], s[38:39], 0, v[138:139]
	s_mov_b32 m0, s37
	s_nop 0
	global_load_lds_dwordx4 v[128:129], off
	v_lshl_add_u64 v[128:129], s[38:39], 0, v[136:137]
	s_add_i32 m0, s37, 0x2000
	s_nop 0
	global_load_lds_dwordx4 v[128:129], off
	s_waitcnt vmcnt(6)
	s_barrier
	s_setprio 1
	v_mfma_f32_16x16x32_bf16 v[52:55], v[212:215], v[180:183], v[52:55]
	v_mfma_f32_16x16x32_bf16 v[48:51], v[220:223], v[180:183], v[48:51]
	v_mfma_f32_16x16x32_bf16 v[36:39], v[212:215], v[188:191], v[36:39]
	v_mfma_f32_16x16x32_bf16 v[32:35], v[220:223], v[188:191], v[32:35]
	v_mfma_f32_16x16x32_bf16 v[20:23], v[212:215], v[196:199], v[20:23]
	v_mfma_f32_16x16x32_bf16 v[16:19], v[220:223], v[196:199], v[16:19]
	v_mfma_f32_16x16x32_bf16 v[4:7], v[212:215], v[204:207], v[4:7]
	v_mfma_f32_16x16x32_bf16 v[0:3], v[220:223], v[204:207], v[0:3]
	v_mfma_f32_16x16x32_bf16 v[52:55], v[216:219], v[184:187], v[52:55]
	v_mfma_f32_16x16x32_bf16 v[48:51], v[224:227], v[184:187], v[48:51]
	v_mfma_f32_16x16x32_bf16 v[36:39], v[216:219], v[192:195], v[36:39]
	v_mfma_f32_16x16x32_bf16 v[32:35], v[224:227], v[192:195], v[32:35]
	v_mfma_f32_16x16x32_bf16 v[20:23], v[216:219], v[200:203], v[20:23]
	v_mfma_f32_16x16x32_bf16 v[16:19], v[224:227], v[200:203], v[16:19]
	v_mfma_f32_16x16x32_bf16 v[4:7], v[216:219], v[208:211], v[4:7]
	v_mfma_f32_16x16x32_bf16 v[0:3], v[224:227], v[208:211], v[0:3]
	s_setprio 0
	s_add_i32 s37, 0, 0x18000
	v_add_u32_e32 v175, s37, v147
	s_barrier
	ds_read_b128 v[128:131], v175
	ds_read_b128 v[132:135], v175 offset:1024
	ds_read_b128 v[164:167], v175 offset:2048
	ds_read_b128 v[176:179], v175 offset:3072
	s_add_u32 s14, s14, 0x40000
	s_addc_u32 s15, s15, 0
	s_mov_b32 m0, s51
	v_lshl_add_u64 v[212:213], s[14:15], 0, v[138:139]
	ds_read_b128 v[180:183], v171 offset:32768
	ds_read_b128 v[184:187], v171 offset:33792
	ds_read_b128 v[188:191], v171 offset:34816
	ds_read_b128 v[192:195], v171 offset:35840
	ds_read_b128 v[196:199], v171 offset:36864
	ds_read_b128 v[200:203], v171 offset:37888
	ds_read_b128 v[204:207], v171 offset:38912
	ds_read_b128 v[208:211], v171 offset:39936
	global_load_lds_dwordx4 v[212:213], off
	v_lshl_add_u64 v[212:213], s[14:15], 0, v[136:137]
	s_mov_b32 m0, s52
	s_nop 0
	global_load_lds_dwordx4 v[212:213], off
	s_waitcnt lgkmcnt(8)
	s_barrier
	s_waitcnt lgkmcnt(0)
	s_setprio 1
	s_waitcnt lgkmcnt(0)
	v_mfma_f32_16x16x32_bf16 v[124:127], v[128:131], v[180:183], v[124:127]
	v_mfma_f32_16x16x32_bf16 v[120:123], v[164:167], v[180:183], v[120:123]
	v_mfma_f32_16x16x32_bf16 v[108:111], v[128:131], v[188:191], v[108:111]
	v_mfma_f32_16x16x32_bf16 v[104:107], v[164:167], v[188:191], v[104:107]
	v_mfma_f32_16x16x32_bf16 v[92:95], v[128:131], v[196:199], v[92:95]
	v_mfma_f32_16x16x32_bf16 v[88:91], v[164:167], v[196:199], v[88:91]
	v_mfma_f32_16x16x32_bf16 v[76:79], v[128:131], v[204:207], v[76:79]
	v_mfma_f32_16x16x32_bf16 v[72:75], v[164:167], v[204:207], v[72:75]
	v_mfma_f32_16x16x32_bf16 v[124:127], v[132:135], v[184:187], v[124:127]
	v_mfma_f32_16x16x32_bf16 v[120:123], v[176:179], v[184:187], v[120:123]
	v_mfma_f32_16x16x32_bf16 v[108:111], v[132:135], v[192:195], v[108:111]
	v_mfma_f32_16x16x32_bf16 v[104:107], v[176:179], v[192:195], v[104:107]
	v_mfma_f32_16x16x32_bf16 v[92:95], v[132:135], v[200:203], v[92:95]
	v_mfma_f32_16x16x32_bf16 v[88:91], v[176:179], v[200:203], v[88:91]
	v_mfma_f32_16x16x32_bf16 v[76:79], v[132:135], v[208:211], v[76:79]
	v_mfma_f32_16x16x32_bf16 v[72:75], v[176:179], v[208:211], v[72:75]
	s_setprio 0
	s_barrier
	s_add_i32 s14, 0, 0x1c000
	s_add_i32 s15, s37, s48
	v_add_u32_e32 v175, s14, v147
	v_lshl_add_u64 v[168:169], v[168:169], 0, s[18:19]
	s_mov_b32 m0, s15
	ds_read_b128 v[212:215], v175
	ds_read_b128 v[216:219], v175 offset:1024
	ds_read_b128 v[220:223], v175 offset:2048
	ds_read_b128 v[224:227], v175 offset:3072
	global_load_lds_dwordx4 v[168:169], off
	v_lshl_add_u64 v[168:169], v[228:229], 0, s[18:19]
	s_add_i32 m0, s15, 0x2000
	s_nop 0
	global_load_lds_dwordx4 v[168:169], off
	s_barrier
	s_waitcnt lgkmcnt(0)
	s_setprio 1
	s_waitcnt lgkmcnt(0)
	v_mfma_f32_16x16x32_bf16 v[116:119], v[212:215], v[180:183], v[116:119]
	v_mfma_f32_16x16x32_bf16 v[112:115], v[220:223], v[180:183], v[112:115]
	v_mfma_f32_16x16x32_bf16 v[100:103], v[212:215], v[188:191], v[100:103]
	v_mfma_f32_16x16x32_bf16 v[96:99], v[220:223], v[188:191], v[96:99]
	v_mfma_f32_16x16x32_bf16 v[84:87], v[212:215], v[196:199], v[84:87]
	v_mfma_f32_16x16x32_bf16 v[80:83], v[220:223], v[196:199], v[80:83]
	v_mfma_f32_16x16x32_bf16 v[68:71], v[212:215], v[204:207], v[68:71]
	v_mfma_f32_16x16x32_bf16 v[64:67], v[220:223], v[204:207], v[64:67]
	v_mfma_f32_16x16x32_bf16 v[116:119], v[216:219], v[184:187], v[116:119]
	v_mfma_f32_16x16x32_bf16 v[112:115], v[224:227], v[184:187], v[112:115]
	v_mfma_f32_16x16x32_bf16 v[100:103], v[216:219], v[192:195], v[100:103]
	v_mfma_f32_16x16x32_bf16 v[96:99], v[224:227], v[192:195], v[96:99]
	v_mfma_f32_16x16x32_bf16 v[84:87], v[216:219], v[200:203], v[84:87]
	v_mfma_f32_16x16x32_bf16 v[80:83], v[224:227], v[200:203], v[80:83]
	v_mfma_f32_16x16x32_bf16 v[68:71], v[216:219], v[208:211], v[68:71]
	v_mfma_f32_16x16x32_bf16 v[64:67], v[224:227], v[208:211], v[64:67]
	s_setprio 0
	s_mov_b32 m0, s56
	v_lshl_add_u64 v[168:169], v[230:231], 0, s[18:19]
	s_barrier
	ds_read_b128 v[180:183], v171 offset:49152
	ds_read_b128 v[184:187], v171 offset:50176
	ds_read_b128 v[188:191], v171 offset:51200
	ds_read_b128 v[192:195], v171 offset:52224
	ds_read_b128 v[196:199], v171 offset:53248
	ds_read_b128 v[200:203], v171 offset:54272
	ds_read_b128 v[204:207], v171 offset:55296
	ds_read_b128 v[208:211], v171 offset:56320
	global_load_lds_dwordx4 v[168:169], off
	v_lshl_add_u64 v[168:169], v[232:233], 0, s[18:19]
	s_mov_b32 m0, s57
	s_nop 0
	global_load_lds_dwordx4 v[168:169], off
	s_barrier
	s_waitcnt lgkmcnt(0)
	s_setprio 1
	s_waitcnt lgkmcnt(0)
	v_mfma_f32_16x16x32_bf16 v[60:63], v[128:131], v[180:183], v[60:63]
	v_mfma_f32_16x16x32_bf16 v[56:59], v[164:167], v[180:183], v[56:59]
	v_mfma_f32_16x16x32_bf16 v[44:47], v[128:131], v[188:191], v[44:47]
	v_mfma_f32_16x16x32_bf16 v[40:43], v[164:167], v[188:191], v[40:43]
	v_mfma_f32_16x16x32_bf16 v[28:31], v[128:131], v[196:199], v[28:31]
	v_mfma_f32_16x16x32_bf16 v[24:27], v[164:167], v[196:199], v[24:27]
	v_mfma_f32_16x16x32_bf16 v[12:15], v[128:131], v[204:207], v[12:15]
	v_mfma_f32_16x16x32_bf16 v[8:11], v[164:167], v[204:207], v[8:11]
	v_mfma_f32_16x16x32_bf16 v[60:63], v[132:135], v[184:187], v[60:63]
	v_mfma_f32_16x16x32_bf16 v[56:59], v[176:179], v[184:187], v[56:59]
	v_mfma_f32_16x16x32_bf16 v[44:47], v[132:135], v[192:195], v[44:47]
	v_mfma_f32_16x16x32_bf16 v[40:43], v[176:179], v[192:195], v[40:43]
	v_mfma_f32_16x16x32_bf16 v[28:31], v[132:135], v[200:203], v[28:31]
	v_mfma_f32_16x16x32_bf16 v[24:27], v[176:179], v[200:203], v[24:27]
	v_mfma_f32_16x16x32_bf16 v[12:15], v[132:135], v[208:211], v[12:15]
	v_mfma_f32_16x16x32_bf16 v[8:11], v[176:179], v[208:211], v[8:11]
	s_setprio 0
	s_barrier
	s_add_u32 s12, s12, 0x40080
	s_addc_u32 s13, s13, 0
	s_add_i32 s14, s14, s48
	v_lshl_add_u64 v[128:129], s[12:13], 0, v[138:139]
	s_mov_b32 m0, s14
	s_nop 0
	global_load_lds_dwordx4 v[128:129], off
	v_lshl_add_u64 v[128:129], s[12:13], 0, v[136:137]
	s_add_i32 m0, s14, 0x2000
	s_nop 0
	global_load_lds_dwordx4 v[128:129], off
	s_waitcnt vmcnt(6)
	s_barrier
	s_setprio 1
	v_mfma_f32_16x16x32_bf16 v[52:55], v[212:215], v[180:183], v[52:55]
	v_mfma_f32_16x16x32_bf16 v[48:51], v[220:223], v[180:183], v[48:51]
	v_mfma_f32_16x16x32_bf16 v[36:39], v[212:215], v[188:191], v[36:39]
	v_mfma_f32_16x16x32_bf16 v[32:35], v[220:223], v[188:191], v[32:35]
	v_mfma_f32_16x16x32_bf16 v[20:23], v[212:215], v[196:199], v[20:23]
	v_mfma_f32_16x16x32_bf16 v[16:19], v[220:223], v[196:199], v[16:19]
	v_mfma_f32_16x16x32_bf16 v[4:7], v[212:215], v[204:207], v[4:7]
	v_mfma_f32_16x16x32_bf16 v[0:3], v[220:223], v[204:207], v[0:3]
	v_mfma_f32_16x16x32_bf16 v[52:55], v[216:219], v[184:187], v[52:55]
	v_mfma_f32_16x16x32_bf16 v[48:51], v[224:227], v[184:187], v[48:51]
	v_mfma_f32_16x16x32_bf16 v[36:39], v[216:219], v[192:195], v[36:39]
	v_mfma_f32_16x16x32_bf16 v[32:35], v[224:227], v[192:195], v[32:35]
	v_mfma_f32_16x16x32_bf16 v[20:23], v[216:219], v[200:203], v[20:23]
	v_mfma_f32_16x16x32_bf16 v[16:19], v[224:227], v[200:203], v[16:19]
	v_mfma_f32_16x16x32_bf16 v[4:7], v[216:219], v[208:211], v[4:7]
	v_mfma_f32_16x16x32_bf16 v[0:3], v[224:227], v[208:211], v[0:3]
	s_setprio 0
	s_add_i32 s36, s36, 2
	s_add_u32 s34, s34, 0x100
	s_addc_u32 s35, s35, 0
	s_add_u32 s10, s10, 0x100
	s_addc_u32 s11, s11, 0
	s_cmp_gt_u32 s36, 13
	s_barrier
	s_cbranch_scc0 .LBB0_1407
	v_mbcnt_lo_u32_b32 v237, -1, 0
	v_mbcnt_hi_u32_b32 v237, -1, v237
	v_bfe_i32 v237, v237, 4, 1
	v_and_b32_e32 v238, 24, v237
	v_mov_b32_e32 v239, 0
	s_lshl_b32 s36, s42, 1
	s_add_i32 s10, s36, 0xffffff80
	s_lshr_b32 s63, s10, 4
	s_lshl_b32 s10, s40, 8
	s_add_i32 s63, s63, 4
	s_ashr_i32 s64, s42, 4
	s_or_b32 s23, s10, s55
	s_and_b32 s10, s40, 0xfffffe
	s_cmp_eq_u32 s10, 6
	s_cselect_b64 s[34:35], -1, 0
	s_cmp_eq_u32 s40, 7
	s_cselect_b64 s[30:31], -1, 0
	s_lshl_b32 s10, s42, 8
	s_cmp_lt_i32 s42, 64
	s_movk_i32 s11, 0xf00
	s_cselect_b32 s11, s11, 0x700
	s_cselect_b32 s12, s64, s63
	s_cselect_b32 s25, s60, 0x800
	s_cselect_b32 s65, 12, 11
	s_and_b32 s66, s11, s10
	s_lshl_b32 s11, s12, 11
	s_lshl_b32 s10, s12, 12
	s_addk_i32 s11, 0x2000
	s_cmp_lt_i32 s12, 4
	s_cselect_b32 s10, s10, s11
	s_ashr_i32 s11, s10, 31
	s_lshl_b64 s[10:11], s[10:11], 10
	s_add_u32 s38, s53, s10
	s_addc_u32 s39, s54, s11
	s_ashr_i32 s37, s36, 31
	v_add_u32_e32 v175, s66, v142
	s_lshl_b64 s[40:41], s[36:37], 7
	v_mul_lo_u32 v130, v175, 56
	s_lshr_b32 s67, s25, 1
	v_lshl_add_u64 v[128:129], s[40:41], 0, v[142:143]
	v_ashrrev_i32_e32 v131, 31, v130
	v_lshl_add_u64 v[168:169], v[130:131], 3, s[16:17]
	v_mad_u64_u32 v[164:165], s[12:13], v128, s61, 0
	s_cmpk_gt_i32 s23, 0x1ff
	v_mad_i32_i24 v165, v129, s61, v165
	v_lshl_add_u64 v[128:129], v[168:169], 0, s[2:3]
	s_cselect_b64 s[14:15], -1, 0
	v_cmp_lt_i32_e64 s[10:11], s67, v175
	v_lshl_add_u64 v[166:167], v[128:129], 0, v[140:141]
	s_mov_b64 s[12:13], -1
	s_and_b64 vcc, exec, s[14:15]
	s_cbranch_vccz .LBB0_1419
	s_cmpk_gt_u32 s23, 0x109f
	s_cbranch_scc1 .LBB0_1418
	s_add_i32 s12, s23, 0xfffffe00
	s_cmpk_gt_u32 s12, 0x1ff
	s_mov_b64 s[42:43], -1
	s_cbranch_scc0 .LBB0_1416
	s_add_i32 s13, s23, 0xfffff700
	s_cmpk_lt_u32 s13, 0x400
	s_cselect_b64 s[42:43], -1, 0
	s_or_b64 s[42:43], s[34:35], s[42:43]
	v_mov_b64_e32 v[134:135], v[126:127]
	v_mov_b64_e32 v[130:131], v[122:123]
	s_andn2_b64 vcc, exec, s[42:43]
	v_mov_b64_e32 v[132:133], v[124:125]
	v_mov_b64_e32 v[128:129], v[120:121]
	s_cbranch_vccnz .LBB0_1415
	s_andn2_b64 vcc, exec, s[20:21]
	v_mov_b32_e32 v128, v124
	v_mov_b32_e32 v129, v125
	v_mov_b32_e32 v130, v126
	v_mov_b32_e32 v131, v127
	s_cbranch_vccnz .LBB0_1414
	v_and_b32_e32 v129, 64, v170
	v_xor_b32_e32 v128, 32, v170
	v_add_u32_e32 v129, 64, v129
	v_cmp_lt_i32_e32 vcc, v128, v129
	v_mov_b32_e32 v129, v141
	s_nop 0
	v_cndmask_b32_e32 v128, v170, v128, vcc
	v_lshlrev_b32_e32 v178, 2, v128
	v_lshlrev_b32_e32 v128, 3, v146
	v_lshl_add_u64 v[132:133], v[168:169], 0, v[128:129]
	s_waitcnt vmcnt(0)
	global_load_dwordx4 v[128:131], v[132:133], off offset:128
	ds_bpermute_b32 v134, v178, v124
	ds_bpermute_b32 v135, v178, v125
	s_waitcnt vmcnt(0) lgkmcnt(0)
	v_mov_b32_e32 v177, v130
	v_mov_b32_e32 v130, v129
	v_mov_b32_e32 v176, v128
	v_pk_mul_f32 v[128:129], v[130:131], v[134:135]
	global_load_dwordx4 v[130:133], v[132:133], off offset:144
	ds_bpermute_b32 v134, v178, v126
	ds_bpermute_b32 v135, v178, v127
	v_cndmask_b32_e64 v129, v129, -v129, s[6:7]
	v_cndmask_b32_e64 v128, v128, -v128, s[6:7]
	v_pk_fma_f32 v[128:129], v[124:125], v[176:177], v[128:129]
	s_waitcnt vmcnt(0) lgkmcnt(0)
	v_mov_b32_e32 v177, v132
	v_mov_b32_e32 v132, v131
	v_mov_b32_e32 v176, v130
	v_pk_mul_f32 v[130:131], v[132:133], v[134:135]
	s_nop 0
	v_cndmask_b32_e64 v131, v131, -v131, s[6:7]
	v_cndmask_b32_e64 v130, v130, -v130, s[6:7]
	v_pk_fma_f32 v[130:131], v[126:127], v[176:177], v[130:131]

.LBB0_1415:
	v_cvt_pk_bf16_f32 v132, v132, v133
	v_cvt_pk_bf16_f32 v133, v134, v135
	v_lshl_add_u64 v[134:135], v[164:165], 1, s[4:5]
	s_mov_b32 s13, s3
	v_lshl_add_u64 v[134:135], s[12:13], 1, v[134:135]
	v_lshlrev_b32_e32 v176, 1, v144
	v_mov_b32_e32 v177, v141
	v_lshl_add_u64 v[134:135], v[134:135], 0, v[176:177]
	v_cvt_pk_bf16_f32 v128, v128, v129
	v_cvt_pk_bf16_f32 v129, v130, v131
	s_mov_b64 s[42:43], 0
	s_waitcnt vmcnt(0)
	v_mov_b32_e32 v244, v132
	v_mov_b32_e32 v245, v133
	v_bfi_b32 v246, v237, v244, v128
	v_bfi_b32 v247, v237, v245, v129
	ds_swizzle_b32 v250, v246 offset:0x401f
	ds_swizzle_b32 v251, v247 offset:0x401f
	v_lshl_add_u64 v[248:249], v[134:135], 0, v[238:239]
	s_waitcnt lgkmcnt(0)
	v_bfi_b32 v240, v237, v250, v244
	v_bfi_b32 v241, v237, v251, v245
	v_bfi_b32 v242, v237, v128, v250
	v_bfi_b32 v243, v237, v129, v251
	global_store_dwordx4 v[248:249], v[240:243], off
	s_nop 1

.LBB0_1432:
	v_cvt_pk_bf16_f32 v122, v122, v123
	v_cvt_pk_bf16_f32 v123, v120, v121
	v_lshl_add_u64 v[120:121], v[164:165], 1, s[4:5]
	s_mov_b32 s11, s3
	v_lshl_add_u64 v[120:121], s[10:11], 1, v[120:121]
	v_lshlrev_b32_e32 v132, 1, v144
	v_mov_b32_e32 v133, v141
	v_lshl_add_u64 v[120:121], v[120:121], 0, v[132:133]
	s_waitcnt vmcnt(0)
	v_mov_b32_e32 v244, v122
	v_mov_b32_e32 v245, v123
	v_cvt_pk_bf16_f32 v122, v126, v127
	v_cvt_pk_bf16_f32 v123, v124, v125
	s_mov_b64 s[12:13], 0
	v_bfi_b32 v246, v237, v244, v122
	v_bfi_b32 v247, v237, v245, v123
	ds_swizzle_b32 v250, v246 offset:0x401f
	ds_swizzle_b32 v251, v247 offset:0x401f
	v_lshl_add_u64 v[248:249], v[120:121], 0, v[238:239]
	s_waitcnt lgkmcnt(0)
	v_bfi_b32 v240, v237, v250, v244
	v_bfi_b32 v241, v237, v251, v245
	v_bfi_b32 v242, v237, v122, v250
	v_bfi_b32 v243, v237, v123, v251
	global_store_dwordx4 v[248:249], v[240:243], off
	s_nop 1

.LBB0_1445:
	v_cvt_pk_bf16_f32 v116, v116, v117
	v_cvt_pk_bf16_f32 v117, v118, v119
	v_lshl_add_u64 v[118:119], v[122:123], 1, s[4:5]
	s_mov_b32 s15, s3
	v_lshl_add_u64 v[118:119], s[14:15], 1, v[118:119]
	v_lshlrev_b32_e32 v130, 1, v144
	v_mov_b32_e32 v131, v141
	v_lshl_add_u64 v[118:119], v[118:119], 0, v[130:131]
	v_cvt_pk_bf16_f32 v112, v112, v113
	v_cvt_pk_bf16_f32 v113, v114, v115
	s_mov_b64 s[44:45], 0
	s_waitcnt vmcnt(0)
	v_mov_b32_e32 v244, v116
	v_mov_b32_e32 v245, v117
	v_bfi_b32 v246, v237, v244, v112
	v_bfi_b32 v247, v237, v245, v113
	ds_swizzle_b32 v250, v246 offset:0x401f
	ds_swizzle_b32 v251, v247 offset:0x401f
	v_lshl_add_u64 v[248:249], v[118:119], 0, v[238:239]
	s_waitcnt lgkmcnt(0)
	v_bfi_b32 v240, v237, v250, v244
	v_bfi_b32 v241, v237, v251, v245
	v_bfi_b32 v242, v237, v112, v250
	v_bfi_b32 v243, v237, v113, v251
	global_store_dwordx4 v[248:249], v[240:243], off
	s_nop 1

.LBB0_1462:
	v_cvt_pk_bf16_f32 v106, v106, v107
	v_cvt_pk_bf16_f32 v107, v104, v105
	v_lshl_add_u64 v[104:105], v[122:123], 1, s[4:5]
	s_mov_b32 s15, s3
	v_lshl_add_u64 v[104:105], s[14:15], 1, v[104:105]
	v_lshlrev_b32_e32 v114, 1, v144
	v_mov_b32_e32 v115, v141
	v_lshl_add_u64 v[104:105], v[104:105], 0, v[114:115]
	s_waitcnt vmcnt(0)
	v_mov_b32_e32 v244, v106
	v_mov_b32_e32 v245, v107
	v_cvt_pk_bf16_f32 v106, v110, v111
	v_cvt_pk_bf16_f32 v107, v108, v109
	s_mov_b64 s[42:43], 0
	v_bfi_b32 v246, v237, v244, v106
	v_bfi_b32 v247, v237, v245, v107
	ds_swizzle_b32 v250, v246 offset:0x401f
	ds_swizzle_b32 v251, v247 offset:0x401f
	v_lshl_add_u64 v[248:249], v[104:105], 0, v[238:239]
	s_waitcnt lgkmcnt(0)
	v_bfi_b32 v240, v237, v250, v244
	v_bfi_b32 v241, v237, v251, v245
	v_bfi_b32 v242, v237, v106, v250
	v_bfi_b32 v243, v237, v107, v251
	global_store_dwordx4 v[248:249], v[240:243], off
	s_nop 1

.LBB0_1475:
	v_cvt_pk_bf16_f32 v100, v100, v101
	v_cvt_pk_bf16_f32 v101, v102, v103
	v_lshl_add_u64 v[102:103], v[104:105], 1, s[4:5]
	s_mov_b32 s43, s3
	v_lshl_add_u64 v[102:103], s[42:43], 1, v[102:103]
	v_lshlrev_b32_e32 v112, 1, v144
	v_mov_b32_e32 v113, v141
	v_lshl_add_u64 v[102:103], v[102:103], 0, v[112:113]
	v_cvt_pk_bf16_f32 v96, v96, v97
	v_cvt_pk_bf16_f32 v97, v98, v99
	s_mov_b64 s[44:45], 0
	s_waitcnt vmcnt(0)
	v_mov_b32_e32 v244, v100
	v_mov_b32_e32 v245, v101
	v_bfi_b32 v246, v237, v244, v96
	v_bfi_b32 v247, v237, v245, v97
	ds_swizzle_b32 v250, v246 offset:0x401f
	ds_swizzle_b32 v251, v247 offset:0x401f
	v_lshl_add_u64 v[248:249], v[102:103], 0, v[238:239]
	s_waitcnt lgkmcnt(0)
	v_bfi_b32 v240, v237, v250, v244
	v_bfi_b32 v241, v237, v251, v245
	v_bfi_b32 v242, v237, v96, v250
	v_bfi_b32 v243, v237, v97, v251
	global_store_dwordx4 v[248:249], v[240:243], off
	s_nop 1

.LBB0_1490:
	v_cvt_pk_bf16_f32 v84, v84, v85
	v_cvt_pk_bf16_f32 v85, v86, v87
	v_lshl_add_u64 v[86:87], v[88:89], 1, s[4:5]
	s_mov_b32 s41, s3
	v_lshl_add_u64 v[86:87], s[40:41], 1, v[86:87]
	v_lshlrev_b32_e32 v96, 1, v144
	v_mov_b32_e32 v97, v141
	v_lshl_add_u64 v[86:87], v[86:87], 0, v[96:97]
	v_cvt_pk_bf16_f32 v80, v80, v81
	v_cvt_pk_bf16_f32 v81, v82, v83
	s_mov_b64 s[42:43], 0
	s_waitcnt vmcnt(0)
	v_mov_b32_e32 v244, v84
	v_mov_b32_e32 v245, v85
	v_bfi_b32 v246, v237, v244, v80
	v_bfi_b32 v247, v237, v245, v81
	ds_swizzle_b32 v250, v246 offset:0x401f
	ds_swizzle_b32 v251, v247 offset:0x401f
	v_lshl_add_u64 v[248:249], v[86:87], 0, v[238:239]
	s_waitcnt lgkmcnt(0)
	v_bfi_b32 v240, v237, v250, v244
	v_bfi_b32 v241, v237, v251, v245
	v_bfi_b32 v242, v237, v80, v250
	v_bfi_b32 v243, v237, v81, v251
	global_store_dwordx4 v[248:249], v[240:243], off
	s_nop 1

.LBB0_1505:
	v_cvt_pk_bf16_f32 v68, v68, v69
	v_cvt_pk_bf16_f32 v69, v70, v71
	v_lshl_add_u64 v[70:71], v[72:73], 1, s[4:5]
	s_mov_b32 s41, s3
	v_lshl_add_u64 v[70:71], s[40:41], 1, v[70:71]
	v_lshlrev_b32_e32 v80, 1, v144
	v_mov_b32_e32 v81, v141
	v_lshl_add_u64 v[70:71], v[70:71], 0, v[80:81]
	v_cvt_pk_bf16_f32 v64, v64, v65
	v_cvt_pk_bf16_f32 v65, v66, v67
	s_mov_b64 s[42:43], 0
	s_waitcnt vmcnt(0)
	v_mov_b32_e32 v244, v68
	v_mov_b32_e32 v245, v69
	v_bfi_b32 v246, v237, v244, v64
	v_bfi_b32 v247, v237, v245, v65
	ds_swizzle_b32 v250, v246 offset:0x401f
	ds_swizzle_b32 v251, v247 offset:0x401f
	v_lshl_add_u64 v[248:249], v[70:71], 0, v[238:239]
	s_waitcnt lgkmcnt(0)
	v_bfi_b32 v240, v237, v250, v244
	v_bfi_b32 v241, v237, v251, v245
	v_bfi_b32 v242, v237, v64, v250
	v_bfi_b32 v243, v237, v65, v251
	global_store_dwordx4 v[248:249], v[240:243], off
	s_nop 1

.LBB0_1520:
	v_cvt_pk_bf16_f32 v52, v52, v53
	v_cvt_pk_bf16_f32 v53, v54, v55
	v_lshl_add_u64 v[54:55], v[56:57], 1, s[4:5]
	s_mov_b32 s41, s3
	v_lshl_add_u64 v[54:55], s[40:41], 1, v[54:55]
	v_lshlrev_b32_e32 v64, 1, v144
	v_mov_b32_e32 v65, v141
	v_lshl_add_u64 v[54:55], v[54:55], 0, v[64:65]
	v_cvt_pk_bf16_f32 v48, v48, v49
	v_cvt_pk_bf16_f32 v49, v50, v51
	s_mov_b64 s[42:43], 0
	s_waitcnt vmcnt(0)
	v_mov_b32_e32 v244, v52
	v_mov_b32_e32 v245, v53
	v_bfi_b32 v246, v237, v244, v48
	v_bfi_b32 v247, v237, v245, v49
	ds_swizzle_b32 v250, v246 offset:0x401f
	ds_swizzle_b32 v251, v247 offset:0x401f
	v_lshl_add_u64 v[248:249], v[54:55], 0, v[238:239]
	s_waitcnt lgkmcnt(0)
	v_bfi_b32 v240, v237, v250, v244
	v_bfi_b32 v241, v237, v251, v245
	v_bfi_b32 v242, v237, v48, v250
	v_bfi_b32 v243, v237, v49, v251
	global_store_dwordx4 v[248:249], v[240:243], off
	s_nop 1

.LBB0_1535:
	v_cvt_pk_bf16_f32 v36, v36, v37
	v_cvt_pk_bf16_f32 v37, v38, v39
	v_lshl_add_u64 v[38:39], v[40:41], 1, s[4:5]
	s_mov_b32 s41, s3
	v_lshl_add_u64 v[38:39], s[40:41], 1, v[38:39]
	v_lshlrev_b32_e32 v48, 1, v144
	v_mov_b32_e32 v49, v141
	v_lshl_add_u64 v[38:39], v[38:39], 0, v[48:49]
	v_cvt_pk_bf16_f32 v32, v32, v33
	v_cvt_pk_bf16_f32 v33, v34, v35
	s_mov_b64 s[42:43], 0
	s_waitcnt vmcnt(0)
	v_mov_b32_e32 v244, v36
	v_mov_b32_e32 v245, v37
	v_bfi_b32 v246, v237, v244, v32
	v_bfi_b32 v247, v237, v245, v33
	ds_swizzle_b32 v250, v246 offset:0x401f
	ds_swizzle_b32 v251, v247 offset:0x401f
	v_lshl_add_u64 v[248:249], v[38:39], 0, v[238:239]
	s_waitcnt lgkmcnt(0)
	v_bfi_b32 v240, v237, v250, v244
	v_bfi_b32 v241, v237, v251, v245
	v_bfi_b32 v242, v237, v32, v250
	v_bfi_b32 v243, v237, v33, v251
	global_store_dwordx4 v[248:249], v[240:243], off
	s_nop 1

.LBB0_1550:
	v_cvt_pk_bf16_f32 v20, v20, v21
	v_cvt_pk_bf16_f32 v21, v22, v23
	v_lshl_add_u64 v[22:23], v[24:25], 1, s[4:5]
	s_mov_b32 s11, s3
	v_lshl_add_u64 v[22:23], s[10:11], 1, v[22:23]
	v_lshlrev_b32_e32 v32, 1, v144
	v_mov_b32_e32 v33, v141
	v_lshl_add_u64 v[22:23], v[22:23], 0, v[32:33]
	v_cvt_pk_bf16_f32 v16, v16, v17
	v_cvt_pk_bf16_f32 v17, v18, v19
	s_mov_b64 s[38:39], 0
	s_waitcnt vmcnt(0)
	v_mov_b32_e32 v244, v20
	v_mov_b32_e32 v245, v21
	v_bfi_b32 v246, v237, v244, v16
	v_bfi_b32 v247, v237, v245, v17
	ds_swizzle_b32 v250, v246 offset:0x401f
	ds_swizzle_b32 v251, v247 offset:0x401f
	v_lshl_add_u64 v[248:249], v[22:23], 0, v[238:239]
	s_waitcnt lgkmcnt(0)
	v_bfi_b32 v240, v237, v250, v244
	v_bfi_b32 v241, v237, v251, v245
	v_bfi_b32 v242, v237, v16, v250
	v_bfi_b32 v243, v237, v17, v251
	global_store_dwordx4 v[248:249], v[240:243], off
	s_nop 1

.LBB0_1568:
	v_cvt_pk_bf16_f32 v90, v90, v91
	v_cvt_pk_bf16_f32 v91, v88, v89
	v_lshl_add_u64 v[88:89], v[104:105], 1, s[4:5]
	s_mov_b32 s15, s3
	v_lshl_add_u64 v[88:89], s[14:15], 1, v[88:89]
	v_lshlrev_b32_e32 v98, 1, v144
	v_mov_b32_e32 v99, v141
	v_lshl_add_u64 v[88:89], v[88:89], 0, v[98:99]
	s_waitcnt vmcnt(0)
	v_mov_b32_e32 v244, v90
	v_mov_b32_e32 v245, v91
	v_cvt_pk_bf16_f32 v90, v94, v95
	v_cvt_pk_bf16_f32 v91, v92, v93
	s_mov_b64 s[42:43], 0
	v_bfi_b32 v246, v237, v244, v90
	v_bfi_b32 v247, v237, v245, v91
	ds_swizzle_b32 v250, v246 offset:0x401f
	ds_swizzle_b32 v251, v247 offset:0x401f
	v_lshl_add_u64 v[248:249], v[88:89], 0, v[238:239]
	s_waitcnt lgkmcnt(0)
	v_bfi_b32 v240, v237, v250, v244
	v_bfi_b32 v241, v237, v251, v245
	v_bfi_b32 v242, v237, v90, v250
	v_bfi_b32 v243, v237, v91, v251
	global_store_dwordx4 v[248:249], v[240:243], off
	s_nop 1

.LBB0_1583:
	v_cvt_pk_bf16_f32 v74, v74, v75
	v_cvt_pk_bf16_f32 v75, v72, v73
	v_lshl_add_u64 v[72:73], v[88:89], 1, s[4:5]
	s_mov_b32 s15, s3
	v_lshl_add_u64 v[72:73], s[14:15], 1, v[72:73]
	v_lshlrev_b32_e32 v82, 1, v144
	v_mov_b32_e32 v83, v141
	v_lshl_add_u64 v[72:73], v[72:73], 0, v[82:83]
	s_waitcnt vmcnt(0)
	v_mov_b32_e32 v244, v74
	v_mov_b32_e32 v245, v75
	v_cvt_pk_bf16_f32 v74, v78, v79
	v_cvt_pk_bf16_f32 v75, v76, v77
	s_mov_b64 s[38:39], 0
	v_bfi_b32 v246, v237, v244, v74
	v_bfi_b32 v247, v237, v245, v75
	ds_swizzle_b32 v250, v246 offset:0x401f
	ds_swizzle_b32 v251, v247 offset:0x401f
	v_lshl_add_u64 v[248:249], v[72:73], 0, v[238:239]
	s_waitcnt lgkmcnt(0)
	v_bfi_b32 v240, v237, v250, v244
	v_bfi_b32 v241, v237, v251, v245
	v_bfi_b32 v242, v237, v74, v250
	v_bfi_b32 v243, v237, v75, v251
	global_store_dwordx4 v[248:249], v[240:243], off
	s_nop 1

.LBB0_1598:
	v_cvt_pk_bf16_f32 v58, v58, v59
	v_cvt_pk_bf16_f32 v59, v56, v57
	v_lshl_add_u64 v[56:57], v[72:73], 1, s[4:5]
	s_mov_b32 s15, s3
	v_lshl_add_u64 v[56:57], s[14:15], 1, v[56:57]
	v_lshlrev_b32_e32 v66, 1, v144
	v_mov_b32_e32 v67, v141
	v_lshl_add_u64 v[56:57], v[56:57], 0, v[66:67]
	s_waitcnt vmcnt(0)
	v_mov_b32_e32 v244, v58
	v_mov_b32_e32 v245, v59
	v_cvt_pk_bf16_f32 v58, v62, v63
	v_cvt_pk_bf16_f32 v59, v60, v61
	s_mov_b64 s[40:41], 0
	v_bfi_b32 v246, v237, v244, v58
	v_bfi_b32 v247, v237, v245, v59
	ds_swizzle_b32 v250, v246 offset:0x401f
	ds_swizzle_b32 v251, v247 offset:0x401f
	v_lshl_add_u64 v[248:249], v[56:57], 0, v[238:239]
	s_waitcnt lgkmcnt(0)
	v_bfi_b32 v240, v237, v250, v244
	v_bfi_b32 v241, v237, v251, v245
	v_bfi_b32 v242, v237, v58, v250
	v_bfi_b32 v243, v237, v59, v251
	global_store_dwordx4 v[248:249], v[240:243], off
	s_nop 1

.LBB0_1613:
	v_cvt_pk_bf16_f32 v42, v42, v43
	v_cvt_pk_bf16_f32 v43, v40, v41
	v_lshl_add_u64 v[40:41], v[56:57], 1, s[4:5]
	s_mov_b32 s15, s3
	v_lshl_add_u64 v[40:41], s[14:15], 1, v[40:41]
	v_lshlrev_b32_e32 v50, 1, v144
	v_mov_b32_e32 v51, v141
	v_lshl_add_u64 v[40:41], v[40:41], 0, v[50:51]
	s_waitcnt vmcnt(0)
	v_mov_b32_e32 v244, v42
	v_mov_b32_e32 v245, v43
	v_cvt_pk_bf16_f32 v42, v46, v47
	v_cvt_pk_bf16_f32 v43, v44, v45
	s_mov_b64 s[40:41], 0
	v_bfi_b32 v246, v237, v244, v42
	v_bfi_b32 v247, v237, v245, v43
	ds_swizzle_b32 v250, v246 offset:0x401f
	ds_swizzle_b32 v251, v247 offset:0x401f
	v_lshl_add_u64 v[248:249], v[40:41], 0, v[238:239]
	s_waitcnt lgkmcnt(0)
	v_bfi_b32 v240, v237, v250, v244
	v_bfi_b32 v241, v237, v251, v245
	v_bfi_b32 v242, v237, v42, v250
	v_bfi_b32 v243, v237, v43, v251
	global_store_dwordx4 v[248:249], v[240:243], off
	s_nop 1

.LBB0_1628:
	v_cvt_pk_bf16_f32 v26, v26, v27
	v_cvt_pk_bf16_f32 v27, v24, v25
	v_lshl_add_u64 v[24:25], v[40:41], 1, s[4:5]
	s_mov_b32 s15, s3
	v_lshl_add_u64 v[24:25], s[14:15], 1, v[24:25]
	v_lshlrev_b32_e32 v34, 1, v144
	v_mov_b32_e32 v35, v141
	v_lshl_add_u64 v[24:25], v[24:25], 0, v[34:35]
	s_waitcnt vmcnt(0)
	v_mov_b32_e32 v244, v26
	v_mov_b32_e32 v245, v27
	v_cvt_pk_bf16_f32 v26, v30, v31
	v_cvt_pk_bf16_f32 v27, v28, v29
	s_mov_b64 s[40:41], 0
	v_bfi_b32 v246, v237, v244, v26
	v_bfi_b32 v247, v237, v245, v27
	ds_swizzle_b32 v250, v246 offset:0x401f
	ds_swizzle_b32 v251, v247 offset:0x401f
	v_lshl_add_u64 v[248:249], v[24:25], 0, v[238:239]
	s_waitcnt lgkmcnt(0)
	v_bfi_b32 v240, v237, v250, v244
	v_bfi_b32 v241, v237, v251, v245
	v_bfi_b32 v242, v237, v26, v250
	v_bfi_b32 v243, v237, v27, v251
	global_store_dwordx4 v[248:249], v[240:243], off
	s_nop 1

.LBB0_1643:
	v_cvt_pk_bf16_f32 v10, v10, v11
	v_cvt_pk_bf16_f32 v11, v8, v9
	v_lshl_add_u64 v[8:9], v[24:25], 1, s[4:5]
	s_mov_b32 s11, s3
	v_lshl_add_u64 v[8:9], s[10:11], 1, v[8:9]
	v_lshlrev_b32_e32 v18, 1, v144
	v_mov_b32_e32 v19, v141
	v_lshl_add_u64 v[8:9], v[8:9], 0, v[18:19]
	s_waitcnt vmcnt(0)
	v_mov_b32_e32 v244, v10
	v_mov_b32_e32 v245, v11
	v_cvt_pk_bf16_f32 v10, v14, v15
	v_cvt_pk_bf16_f32 v11, v12, v13
	s_mov_b64 s[12:13], 0
	v_bfi_b32 v246, v237, v244, v10
	v_bfi_b32 v247, v237, v245, v11
	ds_swizzle_b32 v250, v246 offset:0x401f
	ds_swizzle_b32 v251, v247 offset:0x401f
	v_lshl_add_u64 v[248:249], v[8:9], 0, v[238:239]
	s_waitcnt lgkmcnt(0)
	v_bfi_b32 v240, v237, v250, v244
	v_bfi_b32 v241, v237, v251, v245
	v_bfi_b32 v242, v237, v10, v250
	v_bfi_b32 v243, v237, v11, v251
	global_store_dwordx4 v[248:249], v[240:243], off
	s_nop 1
